# speedup vs baseline: 1.3388x; 1.0064x over previous
; #define LAS __attribute__((address_space(3)))
; template <bool MAPPED>
; __device__ __forceinline__ void transpose_item(const float* W, int K, int Nsrc, bf16_t* WT, const float* gk, LAS float* scr, int item, int nblk, int lane) {
;     const int kb = item / nblk, nb = item % nblk, k0 = 64 * kb, j0 = 32 * nb;
;     const int sc = MAPPED ? in_map(j0 + (lane & 31)) : (j0 + (lane & 31));
; #pragma unroll 8
;     for (int i = 0; i < 32; ++i) { const int kk = 2 * i + (lane >> 5); float v = (sc >= 0) ? W[(size_t)(k0 + kk) * Nsrc + sc] : 0.f; if (gk) v *= gk[k0 + kk]; scr[kk * 33 + (lane & 31)] = v; }
.LBB0_39:
	v_lshl_add_u64 v[48:49], v[46:47], 0, s[0:1]
	global_load_dword v90, v[48:49], off
	v_lshl_add_u64 v[48:49], v[44:45], 0, s[0:1]
	global_load_dword v91, v[48:49], off
	v_lshl_add_u64 v[48:49], v[42:43], 0, s[0:1]
	global_load_dword v92, v[48:49], off
	v_lshl_add_u64 v[48:49], v[40:41], 0, s[0:1]
	global_load_dword v93, v[48:49], off
	v_lshl_add_u64 v[48:49], v[38:39], 0, s[0:1]
	global_load_dword v94, v[48:49], off
	v_lshl_add_u64 v[48:49], v[36:37], 0, s[0:1]
	global_load_dword v95, v[48:49], off
	v_lshl_add_u64 v[48:49], v[34:35], 0, s[0:1]
	global_load_dword v96, v[48:49], off
	v_lshl_add_u64 v[48:49], v[32:33], 0, s[0:1]
	s_add_u32 s0, s0, 0x10000
	s_addc_u32 s1, s1, 0
	global_load_dword v97, v[48:49], off
	v_lshl_add_u64 v[48:49], v[46:47], 0, s[0:1]
	global_load_dword v98, v[48:49], off
	v_lshl_add_u64 v[48:49], v[44:45], 0, s[0:1]
	global_load_dword v99, v[48:49], off
	v_lshl_add_u64 v[48:49], v[42:43], 0, s[0:1]
	global_load_dword v100, v[48:49], off
	v_lshl_add_u64 v[48:49], v[40:41], 0, s[0:1]
	global_load_dword v101, v[48:49], off
	v_lshl_add_u64 v[48:49], v[38:39], 0, s[0:1]
	global_load_dword v102, v[48:49], off
	v_lshl_add_u64 v[48:49], v[36:37], 0, s[0:1]
	global_load_dword v103, v[48:49], off
	v_lshl_add_u64 v[48:49], v[34:35], 0, s[0:1]
	global_load_dword v104, v[48:49], off
	v_lshl_add_u64 v[48:49], v[32:33], 0, s[0:1]
	s_add_u32 s0, s0, 0x10000
	s_addc_u32 s1, s1, 0
	global_load_dword v105, v[48:49], off
	v_lshl_add_u64 v[48:49], v[46:47], 0, s[0:1]
	global_load_dword v110, v[48:49], off
	v_lshl_add_u64 v[48:49], v[44:45], 0, s[0:1]
	global_load_dword v111, v[48:49], off
	v_lshl_add_u64 v[48:49], v[42:43], 0, s[0:1]
	global_load_dword v112, v[48:49], off
	v_lshl_add_u64 v[48:49], v[40:41], 0, s[0:1]
	global_load_dword v113, v[48:49], off
	v_lshl_add_u64 v[48:49], v[38:39], 0, s[0:1]
	global_load_dword v114, v[48:49], off
	v_lshl_add_u64 v[48:49], v[36:37], 0, s[0:1]
	global_load_dword v115, v[48:49], off
	v_lshl_add_u64 v[48:49], v[34:35], 0, s[0:1]
	global_load_dword v116, v[48:49], off
	v_lshl_add_u64 v[48:49], v[32:33], 0, s[0:1]
	s_add_u32 s0, s0, 0x10000
	s_addc_u32 s1, s1, 0
	global_load_dword v117, v[48:49], off
	v_lshl_add_u64 v[48:49], v[46:47], 0, s[0:1]
	global_load_dword v118, v[48:49], off
	v_lshl_add_u64 v[48:49], v[44:45], 0, s[0:1]
	global_load_dword v119, v[48:49], off
	v_lshl_add_u64 v[48:49], v[42:43], 0, s[0:1]
	global_load_dword v120, v[48:49], off
	v_lshl_add_u64 v[48:49], v[40:41], 0, s[0:1]
	global_load_dword v121, v[48:49], off
	v_lshl_add_u64 v[48:49], v[38:39], 0, s[0:1]
	global_load_dword v122, v[48:49], off
	v_lshl_add_u64 v[48:49], v[36:37], 0, s[0:1]
	global_load_dword v123, v[48:49], off
	v_lshl_add_u64 v[48:49], v[34:35], 0, s[0:1]
	global_load_dword v124, v[48:49], off
	v_lshl_add_u64 v[48:49], v[32:33], 0, s[0:1]
	s_add_u32 s0, s0, 0x10000
	s_addc_u32 s1, s1, 0
	global_load_dword v125, v[48:49], off
	s_waitcnt vmcnt(31)
	ds_write_b32 v18, v90
	s_waitcnt vmcnt(30)
	ds_write_b32 v18, v91 offset:264
	s_waitcnt vmcnt(29)
	ds_write_b32 v18, v92 offset:528
	s_waitcnt vmcnt(28)
	ds_write_b32 v18, v93 offset:792
	s_waitcnt vmcnt(27)
	ds_write_b32 v18, v94 offset:1056
	s_waitcnt vmcnt(26)
	ds_write_b32 v18, v95 offset:1320
	s_waitcnt vmcnt(25)
	ds_write_b32 v18, v96 offset:1584
	s_waitcnt vmcnt(24)
	ds_write_b32 v18, v97 offset:1848
	s_waitcnt vmcnt(23)
	ds_write_b32 v18, v98 offset:2112
	s_waitcnt vmcnt(22)
	ds_write_b32 v18, v99 offset:2376
	s_waitcnt vmcnt(21)
	ds_write_b32 v18, v100 offset:2640
	s_waitcnt vmcnt(20)
	ds_write_b32 v18, v101 offset:2904
	s_waitcnt vmcnt(19)
	ds_write_b32 v18, v102 offset:3168
	s_waitcnt vmcnt(18)
	ds_write_b32 v18, v103 offset:3432
	s_waitcnt vmcnt(17)
	ds_write_b32 v18, v104 offset:3696
	s_waitcnt vmcnt(16)
	ds_write_b32 v18, v105 offset:3960
	s_waitcnt vmcnt(15)
	ds_write_b32 v18, v110 offset:4224
	s_waitcnt vmcnt(14)
	ds_write_b32 v18, v111 offset:4488
	s_waitcnt vmcnt(13)
	ds_write_b32 v18, v112 offset:4752
	s_waitcnt vmcnt(12)
	ds_write_b32 v18, v113 offset:5016
	s_waitcnt vmcnt(11)
	ds_write_b32 v18, v114 offset:5280
	s_waitcnt vmcnt(10)
	ds_write_b32 v18, v115 offset:5544
	s_waitcnt vmcnt(9)
	ds_write_b32 v18, v116 offset:5808
	s_waitcnt vmcnt(8)
	ds_write_b32 v18, v117 offset:6072
	s_waitcnt vmcnt(7)
	ds_write_b32 v18, v118 offset:6336
	s_waitcnt vmcnt(6)
	ds_write_b32 v18, v119 offset:6600
	s_waitcnt vmcnt(5)
	ds_write_b32 v18, v120 offset:6864
	s_waitcnt vmcnt(4)
	ds_write_b32 v18, v121 offset:7128
	s_waitcnt vmcnt(3)
	ds_write_b32 v18, v122 offset:7392
	s_waitcnt vmcnt(2)
	ds_write_b32 v18, v123 offset:7656
	s_waitcnt vmcnt(1)
	ds_write_b32 v18, v124 offset:7920
	s_waitcnt vmcnt(0)
	ds_write_b32 v18, v125 offset:8184
	v_add_u32_e32 v18, 0x2100, v18
	s_waitcnt lgkmcnt(0)
; #define LAS __attribute__((address_space(3)))
; __device__ __forceinline__ unsigned pk2(float lo, float hi) { return f2bf(lo) | (f2bf(hi) << 16); }
; template <bool MAPPED>
; __device__ __forceinline__ void transpose_item(const float* W, int K, int Nsrc, bf16_t* WT, const float* gk, LAS float* scr, int item, int nblk, int lane) {
;     ...
;     asm volatile("s_waitcnt lgkmcnt(0)" ::: "memory");
;     const int c = lane & 7;
; #pragma unroll
;     for (int j = 0; j < 4; ++j) { const int n = (lane >> 3) + 8 * j; const LAS float* s = scr + (8 * c) * 33 + n;
;         u32x4 o; o.x = pk2(s[0 * 33], s[1 * 33]); o.y = pk2(s[2 * 33], s[3 * 33]); o.z = pk2(s[4 * 33], s[5 * 33]); o.w = pk2(s[6 * 33], s[7 * 33]);
;         *(u32x4*)(WT + (size_t)(j0 + n) * K + k0 + 8 * c) = o; }
;     asm volatile("s_waitcnt lgkmcnt(0)" ::: "memory");
	ds_read_b32 v18, v57
	ds_read_b32 v32, v57 offset:132
	ds_read_b32 v33, v57 offset:264
	ds_read_b32 v34, v57 offset:396
	ds_read_b32 v35, v57 offset:528
	ds_read_b32 v38, v57 offset:660
	ds_read_b32 v39, v57 offset:792
	ds_read_b32 v40, v57 offset:924
	s_waitcnt lgkmcnt(7)
	v_bfe_u32 v41, v18, 16, 1
	v_add3_u32 v18, v18, v41, s30
	s_waitcnt lgkmcnt(6)
	v_bfe_u32 v41, v32, 16, 1
	v_lshrrev_b32_e32 v18, 16, v18
	v_add3_u32 v32, v32, v41, s30
	v_and_or_b32 v32, v32, s31, v18
	s_waitcnt lgkmcnt(5)
	v_bfe_u32 v18, v33, 16, 1
	v_add3_u32 v18, v33, v18, s30
	s_waitcnt lgkmcnt(4)
	v_bfe_u32 v33, v34, 16, 1
	v_lshrrev_b32_e32 v18, 16, v18
	v_add3_u32 v33, v34, v33, s30
	v_and_or_b32 v33, v33, s31, v18
	s_waitcnt lgkmcnt(3)
	v_bfe_u32 v18, v35, 16, 1
	v_add3_u32 v18, v35, v18, s30
	s_waitcnt lgkmcnt(2)
	v_bfe_u32 v34, v38, 16, 1
	s_lshl_b32 s0, s14, 1
	v_lshrrev_b32_e32 v18, 16, v18
	v_add3_u32 v34, v38, v34, s30
	s_and_b32 s0, s0, 0x7fffffc0
	v_and_or_b32 v34, v34, s31, v18
	s_waitcnt lgkmcnt(1)
	v_bfe_u32 v18, v39, 16, 1
	s_add_i32 s16, s0, 0xffffa900
	s_lshl_b32 s0, s14, 5
	v_add3_u32 v18, v39, v18, s30
	s_waitcnt lgkmcnt(0)
	v_bfe_u32 v35, v40, 16, 1
	s_and_b32 s0, s0, 0x3e0
	v_lshrrev_b32_e32 v18, 16, v18
	v_add3_u32 v35, v40, v35, s30
	v_and_or_b32 v35, v35, s31, v18
	v_or_b32_e32 v18, s0, v17
	v_lshl_add_u64 v[36:37], s[16:17], 1, v[20:21]
	v_mul_u32_u24_e32 v18, 0x1600, v18
	v_lshl_add_u64 v[38:39], v[36:37], 0, v[18:19]
	flat_store_dwordx4 v[38:39], v[32:35]
	ds_read_b32 v18, v57 offset:32
	ds_read_b32 v32, v57 offset:164
	ds_read_b32 v33, v57 offset:296
	ds_read_b32 v34, v57 offset:428
	ds_read_b32 v35, v57 offset:560
	ds_read_b32 v38, v57 offset:692
	ds_read_b32 v39, v57 offset:824
	ds_read_b32 v40, v57 offset:956
	s_waitcnt lgkmcnt(0)
	v_bfe_u32 v41, v18, 16, 1
	v_add3_u32 v18, v18, v41, s30
	v_bfe_u32 v41, v32, 16, 1
	v_lshrrev_b32_e32 v18, 16, v18
	v_add3_u32 v32, v32, v41, s30
	v_and_or_b32 v32, v32, s31, v18
	v_bfe_u32 v18, v33, 16, 1
	v_add3_u32 v18, v33, v18, s30
	v_bfe_u32 v33, v34, 16, 1
	v_lshrrev_b32_e32 v18, 16, v18
	v_add3_u32 v33, v34, v33, s30
	v_and_or_b32 v33, v33, s31, v18
	v_bfe_u32 v18, v35, 16, 1
	v_add3_u32 v18, v35, v18, s30
	v_bfe_u32 v34, v38, 16, 1
	v_lshrrev_b32_e32 v18, 16, v18
	v_add3_u32 v34, v38, v34, s30
	v_and_or_b32 v34, v34, s31, v18
	v_bfe_u32 v18, v39, 16, 1
	v_add3_u32 v18, v39, v18, s30
	v_bfe_u32 v35, v40, 16, 1
	v_lshrrev_b32_e32 v18, 16, v18
	v_add3_u32 v35, v40, v35, s30
	v_and_or_b32 v35, v35, s31, v18
	v_or_b32_e32 v18, s0, v58
	v_mul_u32_u24_e32 v18, 0x1600, v18
	v_lshl_add_u64 v[38:39], v[36:37], 0, v[18:19]
	flat_store_dwordx4 v[38:39], v[32:35]
	ds_read_b32 v18, v57 offset:64
	ds_read_b32 v32, v57 offset:196
	ds_read_b32 v33, v57 offset:328
	ds_read_b32 v34, v57 offset:460
	ds_read_b32 v35, v57 offset:592
	ds_read_b32 v38, v57 offset:724
	ds_read_b32 v39, v57 offset:856
	ds_read_b32 v40, v57 offset:988
	s_waitcnt lgkmcnt(0)
	v_bfe_u32 v41, v18, 16, 1
	v_add3_u32 v18, v18, v41, s30
	v_bfe_u32 v41, v32, 16, 1
	v_lshrrev_b32_e32 v18, 16, v18
	v_add3_u32 v32, v32, v41, s30
	v_and_or_b32 v32, v32, s31, v18
	v_bfe_u32 v18, v33, 16, 1
	v_add3_u32 v18, v33, v18, s30
	v_bfe_u32 v33, v34, 16, 1
	v_lshrrev_b32_e32 v18, 16, v18
	v_add3_u32 v33, v34, v33, s30
	v_and_or_b32 v33, v33, s31, v18
	v_bfe_u32 v18, v35, 16, 1
	v_add3_u32 v18, v35, v18, s30
	v_bfe_u32 v34, v38, 16, 1
	v_lshrrev_b32_e32 v18, 16, v18
	v_add3_u32 v34, v38, v34, s30
	v_and_or_b32 v34, v34, s31, v18
	v_bfe_u32 v18, v39, 16, 1
	v_add3_u32 v18, v39, v18, s30
	v_bfe_u32 v35, v40, 16, 1
	v_lshrrev_b32_e32 v18, 16, v18
	v_add3_u32 v35, v40, v35, s30
	v_and_or_b32 v35, v35, s31, v18
	v_or_b32_e32 v18, s0, v59
	v_mul_u32_u24_e32 v18, 0x1600, v18
	v_lshl_add_u64 v[38:39], v[36:37], 0, v[18:19]
	flat_store_dwordx4 v[38:39], v[32:35]
	ds_read_b32 v18, v57 offset:96
	ds_read_b32 v32, v57 offset:228
	ds_read_b32 v33, v57 offset:360
	ds_read_b32 v34, v57 offset:492
	ds_read_b32 v35, v57 offset:624
	ds_read_b32 v38, v57 offset:756
	ds_read_b32 v39, v57 offset:888
	ds_read_b32 v40, v57 offset:1020
	s_waitcnt lgkmcnt(0)
	v_bfe_u32 v41, v18, 16, 1
	v_add3_u32 v18, v18, v41, s30
	v_bfe_u32 v41, v32, 16, 1
	v_lshrrev_b32_e32 v18, 16, v18
	v_add3_u32 v32, v32, v41, s30
	v_and_or_b32 v32, v32, s31, v18
	v_bfe_u32 v18, v33, 16, 1
	v_add3_u32 v18, v33, v18, s30
	v_bfe_u32 v33, v34, 16, 1
	v_lshrrev_b32_e32 v18, 16, v18
	v_add3_u32 v33, v34, v33, s30
	v_and_or_b32 v33, v33, s31, v18
	v_bfe_u32 v18, v35, 16, 1
	v_add3_u32 v18, v35, v18, s30
	v_bfe_u32 v34, v38, 16, 1
	v_lshrrev_b32_e32 v18, 16, v18
	v_add3_u32 v34, v38, v34, s30
	v_and_or_b32 v34, v34, s31, v18
	v_bfe_u32 v18, v39, 16, 1
	v_add3_u32 v18, v39, v18, s30
	v_bfe_u32 v35, v40, 16, 1
	v_lshrrev_b32_e32 v18, 16, v18
	v_add3_u32 v35, v40, v35, s30
	v_and_or_b32 v35, v35, s31, v18
	v_or_b32_e32 v18, s0, v60
	v_mul_u32_u24_e32 v18, 0x1600, v18
	v_lshl_add_u64 v[36:37], v[36:37], 0, v[18:19]
	flat_store_dwordx4 v[36:37], v[32:35]
	s_waitcnt lgkmcnt(0)
	s_mov_b64 s[0:1], 0

; template <bool MAPPED>
; __device__ __forceinline__ void transpose_item(const float* W, int K, int Nsrc, bf16_t* WT, const float* gk, LAS float* scr, int item, int nblk, int lane) {
;     ...
; #pragma unroll 8
;     for (int i = 0; i < 32; ++i) { const int kk = 2 * i + (lane >> 5); float v = (sc >= 0) ? W[(size_t)(k0 + kk) * Nsrc + sc] : 0.f; if (gk) v *= gk[k0 + kk]; scr[kk * 33 + (lane & 31)] = v; }
.LBB0_43:
	s_add_u32 s8, s8, 0x58000
	s_addc_u32 s9, s9, 0
	v_lshl_add_u64 v[34:35], v[34:35], 0, 64
	v_add_u32_e32 v18, 0x1080, v18
	s_cmp_lg_u32 s8, 0x160000
	s_cbranch_scc0 .LBB0_60
.LBB0_44:
	v_cndmask_b32_e64 v51, 0, 1, s[10:11]
	v_cmp_ne_u32_e64 s[6:7], 1, v51
	s_andn2_b64 vcc, exec, s[10:11]
	s_cbranch_vccnz .Ltq4n
	global_load_dword v110, v[34:35], off
	global_load_dword v111, v[34:35], off offset:8
	global_load_dword v112, v[34:35], off offset:16
	global_load_dword v113, v[34:35], off offset:24
	global_load_dword v114, v[34:35], off offset:32
	global_load_dword v115, v[34:35], off offset:40
	global_load_dword v116, v[34:35], off offset:48
	global_load_dword v117, v[34:35], off offset:56
	global_load_dword v118, v[34:35], off offset:64
	global_load_dword v119, v[34:35], off offset:72
	global_load_dword v120, v[34:35], off offset:80
	global_load_dword v121, v[34:35], off offset:88
	global_load_dword v122, v[34:35], off offset:96
	global_load_dword v123, v[34:35], off offset:104
	global_load_dword v124, v[34:35], off offset:112
	global_load_dword v125, v[34:35], off offset:120
	v_lshl_add_u64 v[50:51], v[38:39], 0, s[8:9]
	global_load_dword v90, v[50:51], off
	v_lshl_add_u64 v[50:51], v[42:43], 0, s[8:9]
	global_load_dword v91, v[50:51], off
	v_lshl_add_u64 v[50:51], v[46:47], 0, s[8:9]
	global_load_dword v92, v[50:51], off
	v_lshl_add_u64 v[50:51], v[48:49], 0, s[8:9]
	global_load_dword v93, v[50:51], off
	v_lshl_add_u64 v[50:51], v[44:45], 0, s[8:9]
	global_load_dword v94, v[50:51], off
	v_lshl_add_u64 v[50:51], v[40:41], 0, s[8:9]
	global_load_dword v95, v[50:51], off
	v_lshl_add_u64 v[50:51], v[36:37], 0, s[8:9]
	global_load_dword v96, v[50:51], off
	v_lshl_add_u64 v[50:51], v[32:33], 0, s[8:9]
	global_load_dword v97, v[50:51], off
	s_add_u32 s8, s8, 0x58000
	s_addc_u32 s9, s9, 0
	v_lshl_add_u64 v[34:35], v[34:35], 0, 64
	v_lshl_add_u64 v[50:51], v[38:39], 0, s[8:9]
	global_load_dword v98, v[50:51], off
	v_lshl_add_u64 v[50:51], v[42:43], 0, s[8:9]
	global_load_dword v99, v[50:51], off
	v_lshl_add_u64 v[50:51], v[46:47], 0, s[8:9]
	global_load_dword v100, v[50:51], off
	v_lshl_add_u64 v[50:51], v[48:49], 0, s[8:9]
	global_load_dword v101, v[50:51], off
	v_lshl_add_u64 v[50:51], v[44:45], 0, s[8:9]
	global_load_dword v102, v[50:51], off
	v_lshl_add_u64 v[50:51], v[40:41], 0, s[8:9]
	global_load_dword v103, v[50:51], off
	v_lshl_add_u64 v[50:51], v[36:37], 0, s[8:9]
	global_load_dword v104, v[50:51], off
	v_lshl_add_u64 v[50:51], v[32:33], 0, s[8:9]
	global_load_dword v105, v[50:51], off
	s_waitcnt vmcnt(15)
	v_mul_f32_e32 v90, v90, v110
	ds_write_b32 v18, v90
	s_waitcnt vmcnt(14)
	v_mul_f32_e32 v91, v91, v111
	ds_write_b32 v18, v91 offset:264
	s_waitcnt vmcnt(13)
	v_mul_f32_e32 v92, v92, v112
	ds_write_b32 v18, v92 offset:528
	s_waitcnt vmcnt(12)
	v_mul_f32_e32 v93, v93, v113
	ds_write_b32 v18, v93 offset:792
	s_waitcnt vmcnt(11)
	v_mul_f32_e32 v94, v94, v114
	ds_write_b32 v18, v94 offset:1056
	s_waitcnt vmcnt(10)
	v_mul_f32_e32 v95, v95, v115
	ds_write_b32 v18, v95 offset:1320
	s_waitcnt vmcnt(9)
	v_mul_f32_e32 v96, v96, v116
	ds_write_b32 v18, v96 offset:1584
	s_waitcnt vmcnt(8)
	v_mul_f32_e32 v97, v97, v117
	ds_write_b32 v18, v97 offset:1848
	s_waitcnt vmcnt(7)
	v_mul_f32_e32 v98, v98, v118
	ds_write_b32 v18, v98 offset:2112
	s_waitcnt vmcnt(6)
	v_mul_f32_e32 v99, v99, v119
	ds_write_b32 v18, v99 offset:2376
	s_waitcnt vmcnt(5)
	v_mul_f32_e32 v100, v100, v120
	ds_write_b32 v18, v100 offset:2640
	s_waitcnt vmcnt(4)
	v_mul_f32_e32 v101, v101, v121
	ds_write_b32 v18, v101 offset:2904
	s_waitcnt vmcnt(3)
	v_mul_f32_e32 v102, v102, v122
	ds_write_b32 v18, v102 offset:3168
	s_waitcnt vmcnt(2)
	v_mul_f32_e32 v103, v103, v123
	ds_write_b32 v18, v103 offset:3432
	s_waitcnt vmcnt(1)
	v_mul_f32_e32 v104, v104, v124
	ds_write_b32 v18, v104 offset:3696
	s_waitcnt vmcnt(0)
	v_mul_f32_e32 v105, v105, v125
	ds_write_b32 v18, v105 offset:3960
	s_branch .LBB0_43
.Ltq4n:
	v_lshl_add_u64 v[50:51], v[38:39], 0, s[8:9]
	global_load_dword v90, v[50:51], off
	v_lshl_add_u64 v[50:51], v[42:43], 0, s[8:9]
	global_load_dword v91, v[50:51], off
	v_lshl_add_u64 v[50:51], v[46:47], 0, s[8:9]
	global_load_dword v92, v[50:51], off
	v_lshl_add_u64 v[50:51], v[48:49], 0, s[8:9]
	global_load_dword v93, v[50:51], off
	v_lshl_add_u64 v[50:51], v[44:45], 0, s[8:9]
	global_load_dword v94, v[50:51], off
	v_lshl_add_u64 v[50:51], v[40:41], 0, s[8:9]
	global_load_dword v95, v[50:51], off
	v_lshl_add_u64 v[50:51], v[36:37], 0, s[8:9]
	global_load_dword v96, v[50:51], off
	v_lshl_add_u64 v[50:51], v[32:33], 0, s[8:9]
	global_load_dword v97, v[50:51], off
	s_add_u32 s8, s8, 0x58000
	s_addc_u32 s9, s9, 0
	v_lshl_add_u64 v[34:35], v[34:35], 0, 64
	v_lshl_add_u64 v[50:51], v[38:39], 0, s[8:9]
	global_load_dword v98, v[50:51], off
	v_lshl_add_u64 v[50:51], v[42:43], 0, s[8:9]
	global_load_dword v99, v[50:51], off
	v_lshl_add_u64 v[50:51], v[46:47], 0, s[8:9]
	global_load_dword v100, v[50:51], off
	v_lshl_add_u64 v[50:51], v[48:49], 0, s[8:9]
	global_load_dword v101, v[50:51], off
	v_lshl_add_u64 v[50:51], v[44:45], 0, s[8:9]
	global_load_dword v102, v[50:51], off
	v_lshl_add_u64 v[50:51], v[40:41], 0, s[8:9]
	global_load_dword v103, v[50:51], off
	v_lshl_add_u64 v[50:51], v[36:37], 0, s[8:9]
	global_load_dword v104, v[50:51], off
	v_lshl_add_u64 v[50:51], v[32:33], 0, s[8:9]
	global_load_dword v105, v[50:51], off
	s_waitcnt vmcnt(15)
	ds_write_b32 v18, v90
	s_waitcnt vmcnt(14)
	ds_write_b32 v18, v91 offset:264
	s_waitcnt vmcnt(13)
	ds_write_b32 v18, v92 offset:528
	s_waitcnt vmcnt(12)
	ds_write_b32 v18, v93 offset:792
	s_waitcnt vmcnt(11)
	ds_write_b32 v18, v94 offset:1056
	s_waitcnt vmcnt(10)
	ds_write_b32 v18, v95 offset:1320
	s_waitcnt vmcnt(9)
	ds_write_b32 v18, v96 offset:1584
	s_waitcnt vmcnt(8)
	ds_write_b32 v18, v97 offset:1848
	s_waitcnt vmcnt(7)
	ds_write_b32 v18, v98 offset:2112
	s_waitcnt vmcnt(6)
	ds_write_b32 v18, v99 offset:2376
	s_waitcnt vmcnt(5)
	ds_write_b32 v18, v100 offset:2640
	s_waitcnt vmcnt(4)
	ds_write_b32 v18, v101 offset:2904
	s_waitcnt vmcnt(3)
	ds_write_b32 v18, v102 offset:3168
	s_waitcnt vmcnt(2)
	ds_write_b32 v18, v103 offset:3432
	s_waitcnt vmcnt(1)
	ds_write_b32 v18, v104 offset:3696
	s_waitcnt vmcnt(0)
	ds_write_b32 v18, v105 offset:3960
	s_branch .LBB0_43

; template <bool MAPPED>
; __device__ __forceinline__ void transpose_item(const float* W, int K, int Nsrc, bf16_t* WT, const float* gk, LAS float* scr, int item, int nblk, int lane) {
;     ...
; #pragma unroll 8
;     for (int i = 0; i < 32; ++i) { const int kk = 2 * i + (lane >> 5); float v = (sc >= 0) ? W[(size_t)(k0 + kk) * Nsrc + sc] : 0.f; if (gk) v *= gk[k0 + kk]; scr[kk * 33 + (lane & 31)] = v; }
.LBB0_64:
	v_lshl_add_u64 v[48:49], v[46:47], 0, s[0:1]
	global_load_dword v90, v[48:49], off
	v_lshl_add_u64 v[48:49], v[44:45], 0, s[0:1]
	global_load_dword v91, v[48:49], off
	v_lshl_add_u64 v[48:49], v[42:43], 0, s[0:1]
	global_load_dword v92, v[48:49], off
	v_lshl_add_u64 v[48:49], v[40:41], 0, s[0:1]
	global_load_dword v93, v[48:49], off
	v_lshl_add_u64 v[48:49], v[38:39], 0, s[0:1]
	global_load_dword v94, v[48:49], off
	v_lshl_add_u64 v[48:49], v[36:37], 0, s[0:1]
	global_load_dword v95, v[48:49], off
	v_lshl_add_u64 v[48:49], v[34:35], 0, s[0:1]
	global_load_dword v96, v[48:49], off
	v_lshl_add_u64 v[48:49], v[32:33], 0, s[0:1]
	s_add_u32 s0, s0, 0x10000
	s_addc_u32 s1, s1, 0
	global_load_dword v97, v[48:49], off
	v_lshl_add_u64 v[48:49], v[46:47], 0, s[0:1]
	global_load_dword v98, v[48:49], off
	v_lshl_add_u64 v[48:49], v[44:45], 0, s[0:1]
	global_load_dword v99, v[48:49], off
	v_lshl_add_u64 v[48:49], v[42:43], 0, s[0:1]
	global_load_dword v100, v[48:49], off
	v_lshl_add_u64 v[48:49], v[40:41], 0, s[0:1]
	global_load_dword v101, v[48:49], off
	v_lshl_add_u64 v[48:49], v[38:39], 0, s[0:1]
	global_load_dword v102, v[48:49], off
	v_lshl_add_u64 v[48:49], v[36:37], 0, s[0:1]
	global_load_dword v103, v[48:49], off
	v_lshl_add_u64 v[48:49], v[34:35], 0, s[0:1]
	global_load_dword v104, v[48:49], off
	v_lshl_add_u64 v[48:49], v[32:33], 0, s[0:1]
	s_add_u32 s0, s0, 0x10000
	s_addc_u32 s1, s1, 0
	global_load_dword v105, v[48:49], off
	v_lshl_add_u64 v[48:49], v[46:47], 0, s[0:1]
	global_load_dword v110, v[48:49], off
	v_lshl_add_u64 v[48:49], v[44:45], 0, s[0:1]
	global_load_dword v111, v[48:49], off
	v_lshl_add_u64 v[48:49], v[42:43], 0, s[0:1]
	global_load_dword v112, v[48:49], off
	v_lshl_add_u64 v[48:49], v[40:41], 0, s[0:1]
	global_load_dword v113, v[48:49], off
	v_lshl_add_u64 v[48:49], v[38:39], 0, s[0:1]
	global_load_dword v114, v[48:49], off
	v_lshl_add_u64 v[48:49], v[36:37], 0, s[0:1]
	global_load_dword v115, v[48:49], off
	v_lshl_add_u64 v[48:49], v[34:35], 0, s[0:1]
	global_load_dword v116, v[48:49], off
	v_lshl_add_u64 v[48:49], v[32:33], 0, s[0:1]
	s_add_u32 s0, s0, 0x10000
	s_addc_u32 s1, s1, 0
	global_load_dword v117, v[48:49], off
	v_lshl_add_u64 v[48:49], v[46:47], 0, s[0:1]
	global_load_dword v118, v[48:49], off
	v_lshl_add_u64 v[48:49], v[44:45], 0, s[0:1]
	global_load_dword v119, v[48:49], off
	v_lshl_add_u64 v[48:49], v[42:43], 0, s[0:1]
	global_load_dword v120, v[48:49], off
	v_lshl_add_u64 v[48:49], v[40:41], 0, s[0:1]
	global_load_dword v121, v[48:49], off
	v_lshl_add_u64 v[48:49], v[38:39], 0, s[0:1]
	global_load_dword v122, v[48:49], off
	v_lshl_add_u64 v[48:49], v[36:37], 0, s[0:1]
	global_load_dword v123, v[48:49], off
	v_lshl_add_u64 v[48:49], v[34:35], 0, s[0:1]
	global_load_dword v124, v[48:49], off
	v_lshl_add_u64 v[48:49], v[32:33], 0, s[0:1]
	s_add_u32 s0, s0, 0x10000
	s_addc_u32 s1, s1, 0
	global_load_dword v125, v[48:49], off
	s_waitcnt vmcnt(31)
	ds_write_b32 v18, v90
	s_waitcnt vmcnt(30)
	ds_write_b32 v18, v91 offset:264
	s_waitcnt vmcnt(29)
	ds_write_b32 v18, v92 offset:528
	s_waitcnt vmcnt(28)
	ds_write_b32 v18, v93 offset:792
	s_waitcnt vmcnt(27)
	ds_write_b32 v18, v94 offset:1056
	s_waitcnt vmcnt(26)
	ds_write_b32 v18, v95 offset:1320
	s_waitcnt vmcnt(25)
	ds_write_b32 v18, v96 offset:1584
	s_waitcnt vmcnt(24)
	ds_write_b32 v18, v97 offset:1848
	s_waitcnt vmcnt(23)
	ds_write_b32 v18, v98 offset:2112
	s_waitcnt vmcnt(22)
	ds_write_b32 v18, v99 offset:2376
	s_waitcnt vmcnt(21)
	ds_write_b32 v18, v100 offset:2640
	s_waitcnt vmcnt(20)
	ds_write_b32 v18, v101 offset:2904
	s_waitcnt vmcnt(19)
	ds_write_b32 v18, v102 offset:3168
	s_waitcnt vmcnt(18)
	ds_write_b32 v18, v103 offset:3432
	s_waitcnt vmcnt(17)
	ds_write_b32 v18, v104 offset:3696
	s_waitcnt vmcnt(16)
	ds_write_b32 v18, v105 offset:3960
	s_waitcnt vmcnt(15)
	ds_write_b32 v18, v110 offset:4224
	s_waitcnt vmcnt(14)
	ds_write_b32 v18, v111 offset:4488
	s_waitcnt vmcnt(13)
	ds_write_b32 v18, v112 offset:4752
	s_waitcnt vmcnt(12)
	ds_write_b32 v18, v113 offset:5016
	s_waitcnt vmcnt(11)
	ds_write_b32 v18, v114 offset:5280
	s_waitcnt vmcnt(10)
	ds_write_b32 v18, v115 offset:5544
	s_waitcnt vmcnt(9)
	ds_write_b32 v18, v116 offset:5808
	s_waitcnt vmcnt(8)
	ds_write_b32 v18, v117 offset:6072
	s_waitcnt vmcnt(7)
	ds_write_b32 v18, v118 offset:6336
	s_waitcnt vmcnt(6)
	ds_write_b32 v18, v119 offset:6600
	s_waitcnt vmcnt(5)
	ds_write_b32 v18, v120 offset:6864
	s_waitcnt vmcnt(4)
	ds_write_b32 v18, v121 offset:7128
	s_waitcnt vmcnt(3)
	ds_write_b32 v18, v122 offset:7392
	s_waitcnt vmcnt(2)
	ds_write_b32 v18, v123 offset:7656
	s_waitcnt vmcnt(1)
	ds_write_b32 v18, v124 offset:7920
	s_waitcnt vmcnt(0)
	ds_write_b32 v18, v125 offset:8184
	v_add_u32_e32 v18, 0x2100, v18
	s_waitcnt lgkmcnt(0)
; #define LAS __attribute__((address_space(3)))
; __device__ __forceinline__ unsigned pk2(float lo, float hi) { return f2bf(lo) | (f2bf(hi) << 16); }
; template <bool MAPPED>
; __device__ __forceinline__ void transpose_item(const float* W, int K, int Nsrc, bf16_t* WT, const float* gk, LAS float* scr, int item, int nblk, int lane) {
;     ...
;     asm volatile("s_waitcnt lgkmcnt(0)" ::: "memory");
;     const int c = lane & 7;
; #pragma unroll
;     for (int j = 0; j < 4; ++j) { const int n = (lane >> 3) + 8 * j; const LAS float* s = scr + (8 * c) * 33 + n;
;         u32x4 o; o.x = pk2(s[0 * 33], s[1 * 33]); o.y = pk2(s[2 * 33], s[3 * 33]); o.z = pk2(s[4 * 33], s[5 * 33]); o.w = pk2(s[6 * 33], s[7 * 33]);
;         *(u32x4*)(WT + (size_t)(j0 + n) * K + k0 + 8 * c) = o; }
;     asm volatile("s_waitcnt lgkmcnt(0)" ::: "memory");
	ds_read_b32 v18, v57
	ds_read_b32 v32, v57 offset:132
	ds_read_b32 v33, v57 offset:264
	ds_read_b32 v34, v57 offset:396
	ds_read_b32 v35, v57 offset:528
	ds_read_b32 v38, v57 offset:660
	ds_read_b32 v39, v57 offset:792
	ds_read_b32 v40, v57 offset:924
	s_waitcnt lgkmcnt(7)
	v_bfe_u32 v41, v18, 16, 1
	v_add3_u32 v18, v18, v41, s30
	s_waitcnt lgkmcnt(6)
	v_bfe_u32 v41, v32, 16, 1
	v_lshrrev_b32_e32 v18, 16, v18
	v_add3_u32 v32, v32, v41, s30
	v_and_or_b32 v32, v32, s31, v18
	s_waitcnt lgkmcnt(5)
	v_bfe_u32 v18, v33, 16, 1
	v_add3_u32 v18, v33, v18, s30
	s_waitcnt lgkmcnt(4)
	v_bfe_u32 v33, v34, 16, 1
	v_lshrrev_b32_e32 v18, 16, v18
	v_add3_u32 v33, v34, v33, s30
	v_and_or_b32 v33, v33, s31, v18
	s_waitcnt lgkmcnt(3)
	v_bfe_u32 v18, v35, 16, 1
	v_add3_u32 v18, v35, v18, s30
	s_waitcnt lgkmcnt(2)
	v_bfe_u32 v34, v38, 16, 1
	s_lshl_b32 s0, s14, 1
	v_lshrrev_b32_e32 v18, 16, v18
	v_add3_u32 v34, v38, v34, s30
	s_add_i32 s0, s0, 0x1c300
	v_and_or_b32 v34, v34, s31, v18
	s_waitcnt lgkmcnt(1)
	v_bfe_u32 v18, v39, 16, 1
	s_and_b32 s1, s0, 0x1ffc0
	s_lshl_b32 s0, s14, 5
	v_add3_u32 v18, v39, v18, s30
	s_waitcnt lgkmcnt(0)
	v_bfe_u32 v35, v40, 16, 1
	s_and_b32 s0, s0, 0x3e0
	v_lshrrev_b32_e32 v18, 16, v18
	v_add3_u32 v35, v40, v35, s30
	s_lshl_b32 s16, s1, 1
	v_and_or_b32 v35, v35, s31, v18
	v_or_b32_e32 v18, s0, v17
	v_lshl_add_u64 v[36:37], v[24:25], 0, s[16:17]
	v_lshlrev_b32_e32 v18, 11, v18
	v_lshl_add_u64 v[38:39], v[36:37], 0, v[18:19]
	flat_store_dwordx4 v[38:39], v[32:35]
	ds_read_b32 v18, v57 offset:32
	ds_read_b32 v32, v57 offset:164
	ds_read_b32 v33, v57 offset:296
	ds_read_b32 v34, v57 offset:428
	ds_read_b32 v35, v57 offset:560
	ds_read_b32 v38, v57 offset:692
	ds_read_b32 v39, v57 offset:824
	ds_read_b32 v40, v57 offset:956
	s_waitcnt lgkmcnt(0)
	v_bfe_u32 v41, v18, 16, 1
	v_add3_u32 v18, v18, v41, s30
	v_bfe_u32 v41, v32, 16, 1
	v_lshrrev_b32_e32 v18, 16, v18
	v_add3_u32 v32, v32, v41, s30
	v_and_or_b32 v32, v32, s31, v18
	v_bfe_u32 v18, v33, 16, 1
	v_add3_u32 v18, v33, v18, s30
	v_bfe_u32 v33, v34, 16, 1
	v_lshrrev_b32_e32 v18, 16, v18
	v_add3_u32 v33, v34, v33, s30
	v_and_or_b32 v33, v33, s31, v18
	v_bfe_u32 v18, v35, 16, 1
	v_add3_u32 v18, v35, v18, s30
	v_bfe_u32 v34, v38, 16, 1
	v_lshrrev_b32_e32 v18, 16, v18
	v_add3_u32 v34, v38, v34, s30
	v_and_or_b32 v34, v34, s31, v18
	v_bfe_u32 v18, v39, 16, 1
	v_add3_u32 v18, v39, v18, s30
	v_bfe_u32 v35, v40, 16, 1
	v_lshrrev_b32_e32 v18, 16, v18
	v_add3_u32 v35, v40, v35, s30
	v_and_or_b32 v35, v35, s31, v18
	v_or_b32_e32 v18, s0, v58
	v_lshlrev_b32_e32 v18, 11, v18
	v_lshl_add_u64 v[38:39], v[36:37], 0, v[18:19]
	flat_store_dwordx4 v[38:39], v[32:35]
	ds_read_b32 v18, v57 offset:64
	ds_read_b32 v32, v57 offset:196
	ds_read_b32 v33, v57 offset:328
	ds_read_b32 v34, v57 offset:460
	ds_read_b32 v35, v57 offset:592
	ds_read_b32 v38, v57 offset:724
	ds_read_b32 v39, v57 offset:856
	ds_read_b32 v40, v57 offset:988
	s_waitcnt lgkmcnt(0)
	v_bfe_u32 v41, v18, 16, 1
	v_add3_u32 v18, v18, v41, s30
	v_bfe_u32 v41, v32, 16, 1
	v_lshrrev_b32_e32 v18, 16, v18
	v_add3_u32 v32, v32, v41, s30
	v_and_or_b32 v32, v32, s31, v18
	v_bfe_u32 v18, v33, 16, 1
	v_add3_u32 v18, v33, v18, s30
	v_bfe_u32 v33, v34, 16, 1
	v_lshrrev_b32_e32 v18, 16, v18
	v_add3_u32 v33, v34, v33, s30
	v_and_or_b32 v33, v33, s31, v18
	v_bfe_u32 v18, v35, 16, 1
	v_add3_u32 v18, v35, v18, s30
	v_bfe_u32 v34, v38, 16, 1
	v_lshrrev_b32_e32 v18, 16, v18
	v_add3_u32 v34, v38, v34, s30
	v_and_or_b32 v34, v34, s31, v18
	v_bfe_u32 v18, v39, 16, 1
	v_add3_u32 v18, v39, v18, s30
	v_bfe_u32 v35, v40, 16, 1
	v_lshrrev_b32_e32 v18, 16, v18
	v_add3_u32 v35, v40, v35, s30
	v_and_or_b32 v35, v35, s31, v18
	v_or_b32_e32 v18, s0, v59
	v_lshlrev_b32_e32 v18, 11, v18
	v_lshl_add_u64 v[38:39], v[36:37], 0, v[18:19]
	flat_store_dwordx4 v[38:39], v[32:35]
	ds_read_b32 v18, v57 offset:96
	ds_read_b32 v32, v57 offset:228
	ds_read_b32 v33, v57 offset:360
	ds_read_b32 v34, v57 offset:492
	ds_read_b32 v35, v57 offset:624
	ds_read_b32 v38, v57 offset:756
	ds_read_b32 v39, v57 offset:888
	ds_read_b32 v40, v57 offset:1020
	s_waitcnt lgkmcnt(0)
	v_bfe_u32 v41, v18, 16, 1
	v_add3_u32 v18, v18, v41, s30
	v_bfe_u32 v41, v32, 16, 1
	v_lshrrev_b32_e32 v18, 16, v18
	v_add3_u32 v32, v32, v41, s30
	v_and_or_b32 v32, v32, s31, v18
	v_bfe_u32 v18, v33, 16, 1
	v_add3_u32 v18, v33, v18, s30
	v_bfe_u32 v33, v34, 16, 1
	v_lshrrev_b32_e32 v18, 16, v18
	v_add3_u32 v33, v34, v33, s30
	v_and_or_b32 v33, v33, s31, v18
	v_bfe_u32 v18, v35, 16, 1
	v_add3_u32 v18, v35, v18, s30
	v_bfe_u32 v34, v38, 16, 1
	v_lshrrev_b32_e32 v18, 16, v18
	v_add3_u32 v34, v38, v34, s30
	v_and_or_b32 v34, v34, s31, v18
	v_bfe_u32 v18, v39, 16, 1
	v_add3_u32 v18, v39, v18, s30
	v_bfe_u32 v35, v40, 16, 1
	v_lshrrev_b32_e32 v18, 16, v18
	v_add3_u32 v35, v40, v35, s30
	v_and_or_b32 v35, v35, s31, v18
	v_or_b32_e32 v18, s0, v60
	v_lshlrev_b32_e32 v18, 11, v18
	v_lshl_add_u64 v[36:37], v[36:37], 0, v[18:19]
	flat_store_dwordx4 v[36:37], v[32:35]
	s_waitcnt lgkmcnt(0)

; template <bool MAPPED>
; __device__ __forceinline__ void transpose_item(const float* W, int K, int Nsrc, bf16_t* WT, const float* gk, LAS float* scr, int item, int nblk, int lane) {
;     ...
; #pragma unroll 8
;     for (int i = 0; i < 32; ++i) { const int kk = 2 * i + (lane >> 5); float v = (sc >= 0) ? W[(size_t)(k0 + kk) * Nsrc + sc] : 0.f; if (gk) v *= gk[k0 + kk]; scr[kk * 33 + (lane & 31)] = v; }
; __device__ __forceinline__ void weights_phase(Frame& F, int layer, int part, int nparts, int gw, int NGW) {
;     ...
;         if (r < 3 * N_BR) { const int n = r / N_BR; transpose_item<false>(w_br + (size_t)n * D * D, D, D, WSP(bf16_t, OFF_WBR + layer * W_LAYER) + (size_t)n * D * D, nullptr, scr, r % N_BR, 32, F.lane); continue; } r -= 3 * N_BR;
.LBB0_69:
	v_lshl_add_u64 v[48:49], v[46:47], 0, s[0:1]
	global_load_dword v90, v[48:49], off
	v_lshl_add_u64 v[48:49], v[44:45], 0, s[0:1]
	global_load_dword v91, v[48:49], off
	v_lshl_add_u64 v[48:49], v[42:43], 0, s[0:1]
	global_load_dword v92, v[48:49], off
	v_lshl_add_u64 v[48:49], v[40:41], 0, s[0:1]
	global_load_dword v93, v[48:49], off
	v_lshl_add_u64 v[48:49], v[38:39], 0, s[0:1]
	global_load_dword v94, v[48:49], off
	v_lshl_add_u64 v[48:49], v[36:37], 0, s[0:1]
	global_load_dword v95, v[48:49], off
	v_lshl_add_u64 v[48:49], v[34:35], 0, s[0:1]
	global_load_dword v96, v[48:49], off
	v_lshl_add_u64 v[48:49], v[32:33], 0, s[0:1]
	s_add_u32 s0, s0, 0x10000
	s_addc_u32 s1, s1, 0
	global_load_dword v97, v[48:49], off
	v_lshl_add_u64 v[48:49], v[46:47], 0, s[0:1]
	global_load_dword v98, v[48:49], off
	v_lshl_add_u64 v[48:49], v[44:45], 0, s[0:1]
	global_load_dword v99, v[48:49], off
	v_lshl_add_u64 v[48:49], v[42:43], 0, s[0:1]
	global_load_dword v100, v[48:49], off
	v_lshl_add_u64 v[48:49], v[40:41], 0, s[0:1]
	global_load_dword v101, v[48:49], off
	v_lshl_add_u64 v[48:49], v[38:39], 0, s[0:1]
	global_load_dword v102, v[48:49], off
	v_lshl_add_u64 v[48:49], v[36:37], 0, s[0:1]
	global_load_dword v103, v[48:49], off
	v_lshl_add_u64 v[48:49], v[34:35], 0, s[0:1]
	global_load_dword v104, v[48:49], off
	v_lshl_add_u64 v[48:49], v[32:33], 0, s[0:1]
	s_add_u32 s0, s0, 0x10000
	s_addc_u32 s1, s1, 0
	global_load_dword v105, v[48:49], off
	v_lshl_add_u64 v[48:49], v[46:47], 0, s[0:1]
	global_load_dword v110, v[48:49], off
	v_lshl_add_u64 v[48:49], v[44:45], 0, s[0:1]
	global_load_dword v111, v[48:49], off
	v_lshl_add_u64 v[48:49], v[42:43], 0, s[0:1]
	global_load_dword v112, v[48:49], off
	v_lshl_add_u64 v[48:49], v[40:41], 0, s[0:1]
	global_load_dword v113, v[48:49], off
	v_lshl_add_u64 v[48:49], v[38:39], 0, s[0:1]
	global_load_dword v114, v[48:49], off
	v_lshl_add_u64 v[48:49], v[36:37], 0, s[0:1]
	global_load_dword v115, v[48:49], off
	v_lshl_add_u64 v[48:49], v[34:35], 0, s[0:1]
	global_load_dword v116, v[48:49], off
	v_lshl_add_u64 v[48:49], v[32:33], 0, s[0:1]
	s_add_u32 s0, s0, 0x10000
	s_addc_u32 s1, s1, 0
	global_load_dword v117, v[48:49], off
	v_lshl_add_u64 v[48:49], v[46:47], 0, s[0:1]
	global_load_dword v118, v[48:49], off
	v_lshl_add_u64 v[48:49], v[44:45], 0, s[0:1]
	global_load_dword v119, v[48:49], off
	v_lshl_add_u64 v[48:49], v[42:43], 0, s[0:1]
	global_load_dword v120, v[48:49], off
	v_lshl_add_u64 v[48:49], v[40:41], 0, s[0:1]
	global_load_dword v121, v[48:49], off
	v_lshl_add_u64 v[48:49], v[38:39], 0, s[0:1]
	global_load_dword v122, v[48:49], off
	v_lshl_add_u64 v[48:49], v[36:37], 0, s[0:1]
	global_load_dword v123, v[48:49], off
	v_lshl_add_u64 v[48:49], v[34:35], 0, s[0:1]
	global_load_dword v124, v[48:49], off
	v_lshl_add_u64 v[48:49], v[32:33], 0, s[0:1]
	s_add_u32 s0, s0, 0x10000
	s_addc_u32 s1, s1, 0
	global_load_dword v125, v[48:49], off
	s_waitcnt vmcnt(31)
	ds_write_b32 v18, v90
	s_waitcnt vmcnt(30)
	ds_write_b32 v18, v91 offset:264
	s_waitcnt vmcnt(29)
	ds_write_b32 v18, v92 offset:528
	s_waitcnt vmcnt(28)
	ds_write_b32 v18, v93 offset:792
	s_waitcnt vmcnt(27)
	ds_write_b32 v18, v94 offset:1056
	s_waitcnt vmcnt(26)
	ds_write_b32 v18, v95 offset:1320
	s_waitcnt vmcnt(25)
	ds_write_b32 v18, v96 offset:1584
	s_waitcnt vmcnt(24)
	ds_write_b32 v18, v97 offset:1848
	s_waitcnt vmcnt(23)
	ds_write_b32 v18, v98 offset:2112
	s_waitcnt vmcnt(22)
	ds_write_b32 v18, v99 offset:2376
	s_waitcnt vmcnt(21)
	ds_write_b32 v18, v100 offset:2640
	s_waitcnt vmcnt(20)
	ds_write_b32 v18, v101 offset:2904
	s_waitcnt vmcnt(19)
	ds_write_b32 v18, v102 offset:3168
	s_waitcnt vmcnt(18)
	ds_write_b32 v18, v103 offset:3432
	s_waitcnt vmcnt(17)
	ds_write_b32 v18, v104 offset:3696
	s_waitcnt vmcnt(16)
	ds_write_b32 v18, v105 offset:3960
	s_waitcnt vmcnt(15)
	ds_write_b32 v18, v110 offset:4224
	s_waitcnt vmcnt(14)
	ds_write_b32 v18, v111 offset:4488
	s_waitcnt vmcnt(13)
	ds_write_b32 v18, v112 offset:4752
	s_waitcnt vmcnt(12)
	ds_write_b32 v18, v113 offset:5016
	s_waitcnt vmcnt(11)
	ds_write_b32 v18, v114 offset:5280
	s_waitcnt vmcnt(10)
	ds_write_b32 v18, v115 offset:5544
	s_waitcnt vmcnt(9)
	ds_write_b32 v18, v116 offset:5808
	s_waitcnt vmcnt(8)
	ds_write_b32 v18, v117 offset:6072
	s_waitcnt vmcnt(7)
	ds_write_b32 v18, v118 offset:6336
	s_waitcnt vmcnt(6)
	ds_write_b32 v18, v119 offset:6600
	s_waitcnt vmcnt(5)
	ds_write_b32 v18, v120 offset:6864
	s_waitcnt vmcnt(4)
	ds_write_b32 v18, v121 offset:7128
	s_waitcnt vmcnt(3)
	ds_write_b32 v18, v122 offset:7392
	s_waitcnt vmcnt(2)
	ds_write_b32 v18, v123 offset:7656
	s_waitcnt vmcnt(1)
	ds_write_b32 v18, v124 offset:7920
	s_waitcnt vmcnt(0)
	ds_write_b32 v18, v125 offset:8184
	v_add_u32_e32 v18, 0x2100, v18
	s_add_i32 s1, s14, 0xffffe780
	s_lshr_b32 s16, s1, 9
	s_lshl_b32 s0, s14, 5
	s_and_b32 s0, s0, 0x3e0
	s_lshl_b64 s[6:7], s[16:17], 21
	s_add_u32 s6, s15, s6
	s_addc_u32 s7, s22, s7
	s_lshl_b32 s1, s1, 2
	s_and_b32 s1, s1, 0x780
	s_add_u32 s6, s6, s1
	s_waitcnt lgkmcnt(0)
; #define LAS __attribute__((address_space(3)))
; __device__ __forceinline__ unsigned pk2(float lo, float hi) { return f2bf(lo) | (f2bf(hi) << 16); }
; template <bool MAPPED>
; __device__ __forceinline__ void transpose_item(const float* W, int K, int Nsrc, bf16_t* WT, const float* gk, LAS float* scr, int item, int nblk, int lane) {
;     ...
;     asm volatile("s_waitcnt lgkmcnt(0)" ::: "memory");
;     const int c = lane & 7;
; #pragma unroll
;     for (int j = 0; j < 4; ++j) { const int n = (lane >> 3) + 8 * j; const LAS float* s = scr + (8 * c) * 33 + n;
;         u32x4 o; o.x = pk2(s[0 * 33], s[1 * 33]); o.y = pk2(s[2 * 33], s[3 * 33]); o.z = pk2(s[4 * 33], s[5 * 33]); o.w = pk2(s[6 * 33], s[7 * 33]);
;         *(u32x4*)(WT + (size_t)(j0 + n) * K + k0 + 8 * c) = o; }
;     asm volatile("s_waitcnt lgkmcnt(0)" ::: "memory");
	s_addc_u32 s7, s7, 0
	v_mov_b32_e32 v31, v19
	v_lshl_add_u64 v[36:37], s[6:7], 0, v[30:31]
	ds_read_b32 v18, v57
	ds_read_b32 v31, v57 offset:132
	ds_read_b32 v33, v57 offset:264
	ds_read_b32 v34, v57 offset:396
	ds_read_b32 v35, v57 offset:528
	ds_read_b32 v38, v57 offset:660
	ds_read_b32 v39, v57 offset:792
	ds_read_b32 v40, v57 offset:924
	s_waitcnt lgkmcnt(7)
	v_bfe_u32 v32, v18, 16, 1
	v_add3_u32 v18, v18, v32, s30
	s_waitcnt lgkmcnt(6)
	v_bfe_u32 v32, v31, 16, 1
	v_lshrrev_b32_e32 v18, 16, v18
	v_add3_u32 v31, v31, v32, s30
	v_and_or_b32 v32, v31, s31, v18
	s_waitcnt lgkmcnt(5)
	v_bfe_u32 v18, v33, 16, 1
	v_add3_u32 v18, v33, v18, s30
	s_waitcnt lgkmcnt(4)
	v_bfe_u32 v31, v34, 16, 1
	v_lshrrev_b32_e32 v18, 16, v18
	v_add3_u32 v31, v34, v31, s30
	v_and_or_b32 v33, v31, s31, v18
	s_waitcnt lgkmcnt(3)
	v_bfe_u32 v18, v35, 16, 1
	v_add3_u32 v18, v35, v18, s30
	s_waitcnt lgkmcnt(2)
	v_bfe_u32 v31, v38, 16, 1
	v_lshrrev_b32_e32 v18, 16, v18
	v_add3_u32 v31, v38, v31, s30
	v_and_or_b32 v34, v31, s31, v18
	s_waitcnt lgkmcnt(1)
	v_bfe_u32 v18, v39, 16, 1
	v_add3_u32 v18, v39, v18, s30
	s_waitcnt lgkmcnt(0)
	v_bfe_u32 v31, v40, 16, 1
	v_lshrrev_b32_e32 v18, 16, v18
	v_add3_u32 v31, v40, v31, s30
	v_and_or_b32 v35, v31, s31, v18
	v_or_b32_e32 v18, s0, v17
	v_lshlrev_b32_e32 v18, 11, v18
	v_lshl_add_u64 v[38:39], v[36:37], 0, v[18:19]
	flat_store_dwordx4 v[38:39], v[32:35]
	ds_read_b32 v18, v57 offset:32
	ds_read_b32 v31, v57 offset:164
	ds_read_b32 v33, v57 offset:296
	ds_read_b32 v34, v57 offset:428
	ds_read_b32 v35, v57 offset:560
	ds_read_b32 v38, v57 offset:692
	ds_read_b32 v39, v57 offset:824
	ds_read_b32 v40, v57 offset:956
	s_waitcnt lgkmcnt(0)
	v_bfe_u32 v32, v18, 16, 1
	v_add3_u32 v18, v18, v32, s30
	v_bfe_u32 v32, v31, 16, 1
	v_lshrrev_b32_e32 v18, 16, v18
	v_add3_u32 v31, v31, v32, s30
	v_and_or_b32 v32, v31, s31, v18
	v_bfe_u32 v18, v33, 16, 1
	v_add3_u32 v18, v33, v18, s30
	v_bfe_u32 v31, v34, 16, 1
	v_lshrrev_b32_e32 v18, 16, v18
	v_add3_u32 v31, v34, v31, s30
	v_and_or_b32 v33, v31, s31, v18
	v_bfe_u32 v18, v35, 16, 1
	v_add3_u32 v18, v35, v18, s30
	v_bfe_u32 v31, v38, 16, 1
	v_lshrrev_b32_e32 v18, 16, v18
	v_add3_u32 v31, v38, v31, s30
	v_and_or_b32 v34, v31, s31, v18
	v_bfe_u32 v18, v39, 16, 1
	v_add3_u32 v18, v39, v18, s30
	v_bfe_u32 v31, v40, 16, 1
	v_lshrrev_b32_e32 v18, 16, v18
	v_add3_u32 v31, v40, v31, s30
	v_and_or_b32 v35, v31, s31, v18
	v_or_b32_e32 v18, s0, v58
	v_lshlrev_b32_e32 v18, 11, v18
	v_lshl_add_u64 v[38:39], v[36:37], 0, v[18:19]
	flat_store_dwordx4 v[38:39], v[32:35]
	ds_read_b32 v18, v57 offset:64
	ds_read_b32 v31, v57 offset:196
	ds_read_b32 v33, v57 offset:328
	ds_read_b32 v34, v57 offset:460
	ds_read_b32 v35, v57 offset:592
	ds_read_b32 v38, v57 offset:724
	ds_read_b32 v39, v57 offset:856
	ds_read_b32 v40, v57 offset:988
	s_waitcnt lgkmcnt(0)
	v_bfe_u32 v32, v18, 16, 1
	v_add3_u32 v18, v18, v32, s30
	v_bfe_u32 v32, v31, 16, 1
	v_lshrrev_b32_e32 v18, 16, v18
	v_add3_u32 v31, v31, v32, s30
	v_and_or_b32 v32, v31, s31, v18
	v_bfe_u32 v18, v33, 16, 1
	v_add3_u32 v18, v33, v18, s30
	v_bfe_u32 v31, v34, 16, 1
	v_lshrrev_b32_e32 v18, 16, v18
	v_add3_u32 v31, v34, v31, s30
	v_and_or_b32 v33, v31, s31, v18
	v_bfe_u32 v18, v35, 16, 1
	v_add3_u32 v18, v35, v18, s30
	v_bfe_u32 v31, v38, 16, 1
	v_lshrrev_b32_e32 v18, 16, v18
	v_add3_u32 v31, v38, v31, s30
	v_and_or_b32 v34, v31, s31, v18
	v_bfe_u32 v18, v39, 16, 1
	v_add3_u32 v18, v39, v18, s30
	v_bfe_u32 v31, v40, 16, 1
	v_lshrrev_b32_e32 v18, 16, v18
	v_add3_u32 v31, v40, v31, s30
	v_and_or_b32 v35, v31, s31, v18
	v_or_b32_e32 v18, s0, v59
	v_lshlrev_b32_e32 v18, 11, v18
	v_lshl_add_u64 v[38:39], v[36:37], 0, v[18:19]
	flat_store_dwordx4 v[38:39], v[32:35]
	ds_read_b32 v18, v57 offset:96
	ds_read_b32 v31, v57 offset:228
	ds_read_b32 v33, v57 offset:360
	ds_read_b32 v34, v57 offset:492
	ds_read_b32 v35, v57 offset:624
	ds_read_b32 v38, v57 offset:756
	ds_read_b32 v39, v57 offset:888
	ds_read_b32 v40, v57 offset:1020
	s_waitcnt lgkmcnt(0)
	v_bfe_u32 v32, v18, 16, 1
	v_add3_u32 v18, v18, v32, s30
	v_bfe_u32 v32, v31, 16, 1
	v_lshrrev_b32_e32 v18, 16, v18
	v_add3_u32 v31, v31, v32, s30
	v_and_or_b32 v32, v31, s31, v18
	v_bfe_u32 v18, v33, 16, 1
	v_add3_u32 v18, v33, v18, s30
	v_bfe_u32 v31, v34, 16, 1
	v_lshrrev_b32_e32 v18, 16, v18
	v_add3_u32 v31, v34, v31, s30
	v_and_or_b32 v33, v31, s31, v18
	v_bfe_u32 v18, v35, 16, 1
	v_add3_u32 v18, v35, v18, s30
	v_bfe_u32 v31, v38, 16, 1
	v_lshrrev_b32_e32 v18, 16, v18
	v_add3_u32 v31, v38, v31, s30
	v_and_or_b32 v34, v31, s31, v18
	v_bfe_u32 v18, v39, 16, 1
	v_add3_u32 v18, v39, v18, s30
	v_bfe_u32 v31, v40, 16, 1
	v_lshrrev_b32_e32 v18, 16, v18
	v_add3_u32 v31, v40, v31, s30
	v_and_or_b32 v35, v31, s31, v18
	v_or_b32_e32 v18, s0, v60
	v_lshlrev_b32_e32 v18, 11, v18
	v_lshl_add_u64 v[36:37], v[36:37], 0, v[18:19]
	flat_store_dwordx4 v[36:37], v[32:35]
	s_waitcnt lgkmcnt(0)

; #define LAS __attribute__((address_space(3)))
; template <bool MAPPED>
; __device__ __forceinline__ void transpose_item(const float* W, int K, int Nsrc, bf16_t* WT, const float* gk, LAS float* scr, int item, int nblk, int lane) {
;     const int kb = item / nblk, nb = item % nblk, k0 = 64 * kb, j0 = 32 * nb;
;     const int sc = MAPPED ? in_map(j0 + (lane & 31)) : (j0 + (lane & 31));
; #pragma unroll 8
;     for (int i = 0; i < 32; ++i) { const int kk = 2 * i + (lane >> 5); float v = (sc >= 0) ? W[(size_t)(k0 + kk) * Nsrc + sc] : 0.f; if (gk) v *= gk[k0 + kk]; scr[kk * 33 + (lane & 31)] = v; }
.LBB0_84:
	s_add_u32 s20, s20, 0xc0600
	s_addc_u32 s21, s21, 0
	v_lshl_add_u64 v[52:53], v[52:53], 0, 64
	v_add_u32_e32 v18, 0x1080, v18
	s_cmp_lg_u32 s20, 0x301800
	s_cbranch_scc0 .LBB0_32
.LBB0_85:
	v_cndmask_b32_e64 v54, 0, 1, s[4:5]
	v_cmp_ne_u32_e64 s[8:9], 1, v54
	s_andn2_b64 vcc, exec, s[4:5]
	s_cbranch_vccnz .Ltq3n
	v_lshl_add_u64 v[54:55], v[52:53], 0, v[48:49]
	global_load_dword v110, v[54:55], off
	v_lshl_add_u64 v[54:55], v[52:53], 0, v[34:35]
	global_load_dword v111, v[54:55], off offset:8
	global_load_dword v112, v[54:55], off offset:16
	global_load_dword v113, v[54:55], off offset:24
	global_load_dword v114, v[54:55], off offset:32
	global_load_dword v115, v[54:55], off offset:40
	global_load_dword v116, v[54:55], off offset:48
	global_load_dword v117, v[54:55], off offset:56
	v_lshl_add_u64 v[54:55], v[52:53], 0, v[48:49]
	global_load_dword v118, v[54:55], off offset:64
	v_lshl_add_u64 v[54:55], v[52:53], 0, v[34:35]
	global_load_dword v119, v[54:55], off offset:72
	global_load_dword v120, v[54:55], off offset:80
	global_load_dword v121, v[54:55], off offset:88
	global_load_dword v122, v[54:55], off offset:96
	global_load_dword v123, v[54:55], off offset:104
	global_load_dword v124, v[54:55], off offset:112
	global_load_dword v125, v[54:55], off offset:120
	v_mov_b32_e32 v90, 0
	v_mov_b32_e32 v91, 0
	v_mov_b32_e32 v92, 0
	v_mov_b32_e32 v93, 0
	v_mov_b32_e32 v94, 0
	v_mov_b32_e32 v95, 0
	v_mov_b32_e32 v96, 0
	v_mov_b32_e32 v97, 0
	s_and_saveexec_b64 s[0:1], s[6:7]
	s_cbranch_execz .Ltq3x0
	v_lshl_add_u64 v[54:55], v[50:51], 0, s[20:21]
	global_load_dword v90, v[54:55], off
	v_lshl_add_u64 v[54:55], v[46:47], 0, s[20:21]
	global_load_dword v91, v[54:55], off
	v_lshl_add_u64 v[78:79], v[44:45], 0, s[20:21]
	global_load_dword v92, v[78:79], off
	v_lshl_add_u64 v[78:79], v[42:43], 0, s[20:21]
	global_load_dword v93, v[78:79], off
	v_lshl_add_u64 v[78:79], v[40:41], 0, s[20:21]
	global_load_dword v94, v[78:79], off
	v_lshl_add_u64 v[78:79], v[38:39], 0, s[20:21]
	global_load_dword v95, v[78:79], off
	v_lshl_add_u64 v[78:79], v[36:37], 0, s[20:21]
	global_load_dword v96, v[78:79], off
	v_lshl_add_u64 v[78:79], v[32:33], 0, s[20:21]
	global_load_dword v97, v[78:79], off
.Ltq3x0:
	s_or_b64 exec, exec, s[0:1]
	s_add_u32 s20, s20, 0xc0600
	s_addc_u32 s21, s21, 0
	v_lshl_add_u64 v[52:53], v[52:53], 0, 64
	v_mov_b32_e32 v98, 0
	v_mov_b32_e32 v99, 0
	v_mov_b32_e32 v100, 0
	v_mov_b32_e32 v101, 0
	v_mov_b32_e32 v102, 0
	v_mov_b32_e32 v103, 0
	v_mov_b32_e32 v104, 0
	v_mov_b32_e32 v105, 0
	s_and_saveexec_b64 s[0:1], s[6:7]
	s_cbranch_execz .Ltq3x1
	v_lshl_add_u64 v[54:55], v[50:51], 0, s[20:21]
	global_load_dword v98, v[54:55], off
	v_lshl_add_u64 v[54:55], v[46:47], 0, s[20:21]
	global_load_dword v99, v[54:55], off
	v_lshl_add_u64 v[78:79], v[44:45], 0, s[20:21]
	global_load_dword v100, v[78:79], off
	v_lshl_add_u64 v[78:79], v[42:43], 0, s[20:21]
	global_load_dword v101, v[78:79], off
	v_lshl_add_u64 v[78:79], v[40:41], 0, s[20:21]
	global_load_dword v102, v[78:79], off
	v_lshl_add_u64 v[78:79], v[38:39], 0, s[20:21]
	global_load_dword v103, v[78:79], off
	v_lshl_add_u64 v[78:79], v[36:37], 0, s[20:21]
	global_load_dword v104, v[78:79], off
	v_lshl_add_u64 v[78:79], v[32:33], 0, s[20:21]
	global_load_dword v105, v[78:79], off
.Ltq3x1:
	s_or_b64 exec, exec, s[0:1]
	s_waitcnt vmcnt(15)
	v_mul_f32_e32 v90, v90, v110
	ds_write_b32 v18, v90
	s_waitcnt vmcnt(14)
	v_mul_f32_e32 v91, v91, v111
	ds_write_b32 v18, v91 offset:264
	s_waitcnt vmcnt(13)
	v_mul_f32_e32 v92, v92, v112
	ds_write_b32 v18, v92 offset:528
	s_waitcnt vmcnt(12)
	v_mul_f32_e32 v93, v93, v113
	ds_write_b32 v18, v93 offset:792
	s_waitcnt vmcnt(11)
	v_mul_f32_e32 v94, v94, v114
	ds_write_b32 v18, v94 offset:1056
	s_waitcnt vmcnt(10)
	v_mul_f32_e32 v95, v95, v115
	ds_write_b32 v18, v95 offset:1320
	s_waitcnt vmcnt(9)
	v_mul_f32_e32 v96, v96, v116
	ds_write_b32 v18, v96 offset:1584
	s_waitcnt vmcnt(8)
	v_mul_f32_e32 v97, v97, v117
	ds_write_b32 v18, v97 offset:1848
	s_waitcnt vmcnt(7)
	v_mul_f32_e32 v98, v98, v118
	ds_write_b32 v18, v98 offset:2112
	s_waitcnt vmcnt(6)
	v_mul_f32_e32 v99, v99, v119
	ds_write_b32 v18, v99 offset:2376
	s_waitcnt vmcnt(5)
	v_mul_f32_e32 v100, v100, v120
	ds_write_b32 v18, v100 offset:2640
	s_waitcnt vmcnt(4)
	v_mul_f32_e32 v101, v101, v121
	ds_write_b32 v18, v101 offset:2904
	s_waitcnt vmcnt(3)
	v_mul_f32_e32 v102, v102, v122
	ds_write_b32 v18, v102 offset:3168
	s_waitcnt vmcnt(2)
	v_mul_f32_e32 v103, v103, v123
	ds_write_b32 v18, v103 offset:3432
	s_waitcnt vmcnt(1)
	v_mul_f32_e32 v104, v104, v124
	ds_write_b32 v18, v104 offset:3696
	s_waitcnt vmcnt(0)
	v_mul_f32_e32 v105, v105, v125
	ds_write_b32 v18, v105 offset:3960
	s_branch .LBB0_84
.Ltq3n:
	v_mov_b32_e32 v90, 0
	v_mov_b32_e32 v91, 0
	v_mov_b32_e32 v92, 0
	v_mov_b32_e32 v93, 0
	v_mov_b32_e32 v94, 0
	v_mov_b32_e32 v95, 0
	v_mov_b32_e32 v96, 0
	v_mov_b32_e32 v97, 0
	s_and_saveexec_b64 s[0:1], s[6:7]
	s_cbranch_execz .Ltq3y0
	v_lshl_add_u64 v[54:55], v[50:51], 0, s[20:21]
	global_load_dword v90, v[54:55], off
	v_lshl_add_u64 v[54:55], v[46:47], 0, s[20:21]
	global_load_dword v91, v[54:55], off
	v_lshl_add_u64 v[78:79], v[44:45], 0, s[20:21]
	global_load_dword v92, v[78:79], off
	v_lshl_add_u64 v[78:79], v[42:43], 0, s[20:21]
	global_load_dword v93, v[78:79], off
	v_lshl_add_u64 v[78:79], v[40:41], 0, s[20:21]
	global_load_dword v94, v[78:79], off
	v_lshl_add_u64 v[78:79], v[38:39], 0, s[20:21]
	global_load_dword v95, v[78:79], off
	v_lshl_add_u64 v[78:79], v[36:37], 0, s[20:21]
	global_load_dword v96, v[78:79], off
	v_lshl_add_u64 v[78:79], v[32:33], 0, s[20:21]
	global_load_dword v97, v[78:79], off

; template <bool MAPPED>
; __device__ __forceinline__ void transpose_item(const float* W, int K, int Nsrc, bf16_t* WT, const float* gk, LAS float* scr, int item, int nblk, int lane) {
;     ...
; #pragma unroll 8
;     for (int i = 0; i < 32; ++i) { const int kk = 2 * i + (lane >> 5); float v = (sc >= 0) ? W[(size_t)(k0 + kk) * Nsrc + sc] : 0.f; if (gk) v *= gk[k0 + kk]; scr[kk * 33 + (lane & 31)] = v; }
.Ltq3y1:
	s_or_b64 exec, exec, s[0:1]
	s_waitcnt vmcnt(15)
	ds_write_b32 v18, v90
	s_waitcnt vmcnt(14)
	ds_write_b32 v18, v91 offset:264
	s_waitcnt vmcnt(13)
	ds_write_b32 v18, v92 offset:528
	s_waitcnt vmcnt(12)
	ds_write_b32 v18, v93 offset:792
	s_waitcnt vmcnt(11)
	ds_write_b32 v18, v94 offset:1056
	s_waitcnt vmcnt(10)
	ds_write_b32 v18, v95 offset:1320
	s_waitcnt vmcnt(9)
	ds_write_b32 v18, v96 offset:1584
	s_waitcnt vmcnt(8)
	ds_write_b32 v18, v97 offset:1848
	s_waitcnt vmcnt(7)
	ds_write_b32 v18, v98 offset:2112
	s_waitcnt vmcnt(6)
	ds_write_b32 v18, v99 offset:2376
	s_waitcnt vmcnt(5)
	ds_write_b32 v18, v100 offset:2640
	s_waitcnt vmcnt(4)
	ds_write_b32 v18, v101 offset:2904
	s_waitcnt vmcnt(3)
	ds_write_b32 v18, v102 offset:3168
	s_waitcnt vmcnt(2)
	ds_write_b32 v18, v103 offset:3432
	s_waitcnt vmcnt(1)
	ds_write_b32 v18, v104 offset:3696
	s_waitcnt vmcnt(0)
	ds_write_b32 v18, v105 offset:3960
	s_branch .LBB0_84

; template <bool MAPPED>
; __device__ __forceinline__ void transpose_item(const float* W, int K, int Nsrc, bf16_t* WT, const float* gk, LAS float* scr, int item, int nblk, int lane) {
;     ...
; #pragma unroll 8
;     for (int i = 0; i < 32; ++i) { const int kk = 2 * i + (lane >> 5); float v = (sc >= 0) ? W[(size_t)(k0 + kk) * Nsrc + sc] : 0.f; if (gk) v *= gk[k0 + kk]; scr[kk * 33 + (lane & 31)] = v; }
.LBB0_805:
	v_add_u32_e32 v33, s1, v32
	v_add_u32_e32 v34, 0xffffa900, v33
	v_ashrrev_i32_e32 v35, 31, v34
	v_lshlrev_b64 v[34:35], 12, v[34:35]
	v_lshl_add_u64 v[34:35], v[30:31], 0, v[34:35]
	global_load_dword v90, v[34:35], off
	s_add_i32 s1, s1, 16
	v_add_u32_e32 v34, 0xffffa902, v33
	v_ashrrev_i32_e32 v35, 31, v34
	v_lshlrev_b64 v[34:35], 12, v[34:35]
	v_lshl_add_u64 v[34:35], v[30:31], 0, v[34:35]
	global_load_dword v91, v[34:35], off
	v_add_u32_e32 v34, 0xffffa904, v33
	v_ashrrev_i32_e32 v35, 31, v34
	v_lshlrev_b64 v[34:35], 12, v[34:35]
	v_lshl_add_u64 v[34:35], v[30:31], 0, v[34:35]
	global_load_dword v92, v[34:35], off
	v_add_u32_e32 v34, 0xffffa906, v33
	v_ashrrev_i32_e32 v35, 31, v34
	v_lshlrev_b64 v[34:35], 12, v[34:35]
	v_lshl_add_u64 v[34:35], v[30:31], 0, v[34:35]
	global_load_dword v93, v[34:35], off
	v_add_u32_e32 v34, 0xffffa908, v33
	v_ashrrev_i32_e32 v35, 31, v34
	v_lshlrev_b64 v[34:35], 12, v[34:35]
	v_lshl_add_u64 v[34:35], v[30:31], 0, v[34:35]
	global_load_dword v94, v[34:35], off
	v_add_u32_e32 v34, 0xffffa90a, v33
	v_ashrrev_i32_e32 v35, 31, v34
	v_lshlrev_b64 v[34:35], 12, v[34:35]
	v_lshl_add_u64 v[34:35], v[30:31], 0, v[34:35]
	global_load_dword v95, v[34:35], off
	v_add_u32_e32 v34, 0xffffa90c, v33
	v_ashrrev_i32_e32 v35, 31, v34
	v_lshlrev_b64 v[34:35], 12, v[34:35]
	v_lshl_add_u64 v[34:35], v[30:31], 0, v[34:35]
	global_load_dword v96, v[34:35], off
	v_add_u32_e32 v34, 0xffffa90e, v33
	v_ashrrev_i32_e32 v35, 31, v34
	v_lshlrev_b64 v[34:35], 12, v[34:35]
	v_lshl_add_u64 v[34:35], v[30:31], 0, v[34:35]
	global_load_dword v97, v[34:35], off
	v_add_u32_e32 v33, s1, v32
	v_add_u32_e32 v34, 0xffffa900, v33
	v_ashrrev_i32_e32 v35, 31, v34
	v_lshlrev_b64 v[34:35], 12, v[34:35]
	v_lshl_add_u64 v[34:35], v[30:31], 0, v[34:35]
	global_load_dword v98, v[34:35], off
	s_add_i32 s1, s1, 16
	v_add_u32_e32 v34, 0xffffa902, v33
	v_ashrrev_i32_e32 v35, 31, v34
	v_lshlrev_b64 v[34:35], 12, v[34:35]
	v_lshl_add_u64 v[34:35], v[30:31], 0, v[34:35]
	global_load_dword v99, v[34:35], off
	v_add_u32_e32 v34, 0xffffa904, v33
	v_ashrrev_i32_e32 v35, 31, v34
	v_lshlrev_b64 v[34:35], 12, v[34:35]
	v_lshl_add_u64 v[34:35], v[30:31], 0, v[34:35]
	global_load_dword v100, v[34:35], off
	v_add_u32_e32 v34, 0xffffa906, v33
	v_ashrrev_i32_e32 v35, 31, v34
	v_lshlrev_b64 v[34:35], 12, v[34:35]
	v_lshl_add_u64 v[34:35], v[30:31], 0, v[34:35]
	global_load_dword v101, v[34:35], off
	v_add_u32_e32 v34, 0xffffa908, v33
	v_ashrrev_i32_e32 v35, 31, v34
	v_lshlrev_b64 v[34:35], 12, v[34:35]
	v_lshl_add_u64 v[34:35], v[30:31], 0, v[34:35]
	global_load_dword v102, v[34:35], off
	v_add_u32_e32 v34, 0xffffa90a, v33
	v_ashrrev_i32_e32 v35, 31, v34
	v_lshlrev_b64 v[34:35], 12, v[34:35]
	v_lshl_add_u64 v[34:35], v[30:31], 0, v[34:35]
	global_load_dword v103, v[34:35], off
	v_add_u32_e32 v34, 0xffffa90c, v33
	v_ashrrev_i32_e32 v35, 31, v34
	v_lshlrev_b64 v[34:35], 12, v[34:35]
	v_lshl_add_u64 v[34:35], v[30:31], 0, v[34:35]
	global_load_dword v104, v[34:35], off
	v_add_u32_e32 v34, 0xffffa90e, v33
	v_ashrrev_i32_e32 v35, 31, v34
	v_lshlrev_b64 v[34:35], 12, v[34:35]
	v_lshl_add_u64 v[34:35], v[30:31], 0, v[34:35]
	global_load_dword v105, v[34:35], off
	v_add_u32_e32 v33, s1, v32
	v_add_u32_e32 v34, 0xffffa900, v33
	v_ashrrev_i32_e32 v35, 31, v34
	v_lshlrev_b64 v[34:35], 12, v[34:35]
	v_lshl_add_u64 v[34:35], v[30:31], 0, v[34:35]
	global_load_dword v110, v[34:35], off
	s_add_i32 s1, s1, 16
	v_add_u32_e32 v34, 0xffffa902, v33
	v_ashrrev_i32_e32 v35, 31, v34
	v_lshlrev_b64 v[34:35], 12, v[34:35]
	v_lshl_add_u64 v[34:35], v[30:31], 0, v[34:35]
	global_load_dword v111, v[34:35], off
	v_add_u32_e32 v34, 0xffffa904, v33
	v_ashrrev_i32_e32 v35, 31, v34
	v_lshlrev_b64 v[34:35], 12, v[34:35]
	v_lshl_add_u64 v[34:35], v[30:31], 0, v[34:35]
	global_load_dword v112, v[34:35], off
	v_add_u32_e32 v34, 0xffffa906, v33
	v_ashrrev_i32_e32 v35, 31, v34
	v_lshlrev_b64 v[34:35], 12, v[34:35]
	v_lshl_add_u64 v[34:35], v[30:31], 0, v[34:35]
	global_load_dword v113, v[34:35], off
	v_add_u32_e32 v34, 0xffffa908, v33
	v_ashrrev_i32_e32 v35, 31, v34
	v_lshlrev_b64 v[34:35], 12, v[34:35]
	v_lshl_add_u64 v[34:35], v[30:31], 0, v[34:35]
	global_load_dword v114, v[34:35], off
	v_add_u32_e32 v34, 0xffffa90a, v33
	v_ashrrev_i32_e32 v35, 31, v34
	v_lshlrev_b64 v[34:35], 12, v[34:35]
	v_lshl_add_u64 v[34:35], v[30:31], 0, v[34:35]
	global_load_dword v115, v[34:35], off
	v_add_u32_e32 v34, 0xffffa90c, v33
	v_ashrrev_i32_e32 v35, 31, v34
	v_lshlrev_b64 v[34:35], 12, v[34:35]
	v_lshl_add_u64 v[34:35], v[30:31], 0, v[34:35]
	global_load_dword v116, v[34:35], off
	v_add_u32_e32 v34, 0xffffa90e, v33
	v_ashrrev_i32_e32 v35, 31, v34
	v_lshlrev_b64 v[34:35], 12, v[34:35]
	v_lshl_add_u64 v[34:35], v[30:31], 0, v[34:35]
	global_load_dword v117, v[34:35], off
	v_add_u32_e32 v33, s1, v32
	v_add_u32_e32 v34, 0xffffa900, v33
	v_ashrrev_i32_e32 v35, 31, v34
	v_lshlrev_b64 v[34:35], 12, v[34:35]
	v_lshl_add_u64 v[34:35], v[30:31], 0, v[34:35]
	global_load_dword v118, v[34:35], off
	s_add_i32 s1, s1, 16
	v_add_u32_e32 v34, 0xffffa902, v33
	v_ashrrev_i32_e32 v35, 31, v34
	v_lshlrev_b64 v[34:35], 12, v[34:35]
	v_lshl_add_u64 v[34:35], v[30:31], 0, v[34:35]
	global_load_dword v119, v[34:35], off
	v_add_u32_e32 v34, 0xffffa904, v33
	v_ashrrev_i32_e32 v35, 31, v34
	v_lshlrev_b64 v[34:35], 12, v[34:35]
	v_lshl_add_u64 v[34:35], v[30:31], 0, v[34:35]
	global_load_dword v120, v[34:35], off
	v_add_u32_e32 v34, 0xffffa906, v33
	v_ashrrev_i32_e32 v35, 31, v34
	v_lshlrev_b64 v[34:35], 12, v[34:35]
	v_lshl_add_u64 v[34:35], v[30:31], 0, v[34:35]
	global_load_dword v121, v[34:35], off
	v_add_u32_e32 v34, 0xffffa908, v33
	v_ashrrev_i32_e32 v35, 31, v34
	v_lshlrev_b64 v[34:35], 12, v[34:35]
	v_lshl_add_u64 v[34:35], v[30:31], 0, v[34:35]
	global_load_dword v122, v[34:35], off
	v_add_u32_e32 v34, 0xffffa90a, v33
	v_ashrrev_i32_e32 v35, 31, v34
	v_lshlrev_b64 v[34:35], 12, v[34:35]
	v_lshl_add_u64 v[34:35], v[30:31], 0, v[34:35]
	global_load_dword v123, v[34:35], off
	v_add_u32_e32 v34, 0xffffa90c, v33
	v_ashrrev_i32_e32 v35, 31, v34
	v_lshlrev_b64 v[34:35], 12, v[34:35]
	v_lshl_add_u64 v[34:35], v[30:31], 0, v[34:35]
	global_load_dword v124, v[34:35], off
	v_add_u32_e32 v34, 0xffffa90e, v33
	v_ashrrev_i32_e32 v35, 31, v34
	v_lshlrev_b64 v[34:35], 12, v[34:35]
	v_lshl_add_u64 v[34:35], v[30:31], 0, v[34:35]
	global_load_dword v125, v[34:35], off
	s_waitcnt vmcnt(31)
; #define LAS __attribute__((address_space(3)))
; __device__ __forceinline__ unsigned pk2(float lo, float hi) { return f2bf(lo) | (f2bf(hi) << 16); }
; template <bool MAPPED>
; __device__ __forceinline__ void transpose_item(const float* W, int K, int Nsrc, bf16_t* WT, const float* gk, LAS float* scr, int item, int nblk, int lane) {
;     ...
;     for (int i = 0; i < 32; ++i) { const int kk = 2 * i + (lane >> 5); float v = (sc >= 0) ? W[(size_t)(k0 + kk) * Nsrc + sc] : 0.f; if (gk) v *= gk[k0 + kk]; scr[kk * 33 + (lane & 31)] = v; }
;     asm volatile("s_waitcnt lgkmcnt(0)" ::: "memory");
;     const int c = lane & 7;
; #pragma unroll
;     for (int j = 0; j < 4; ++j) { const int n = (lane >> 3) + 8 * j; const LAS float* s = scr + (8 * c) * 33 + n;
;         u32x4 o; o.x = pk2(s[0 * 33], s[1 * 33]); o.y = pk2(s[2 * 33], s[3 * 33]); o.z = pk2(s[4 * 33], s[5 * 33]); o.w = pk2(s[6 * 33], s[7 * 33]);
;         *(u32x4*)(WT + (size_t)(j0 + n) * K + k0 + 8 * c) = o; }
;     asm volatile("s_waitcnt lgkmcnt(0)" ::: "memory");
	ds_write_b32 v0, v90
	s_waitcnt vmcnt(30)
	ds_write_b32 v0, v91 offset:264
	s_waitcnt vmcnt(29)
	ds_write_b32 v0, v92 offset:528
	s_waitcnt vmcnt(28)
	ds_write_b32 v0, v93 offset:792
	s_waitcnt vmcnt(27)
	ds_write_b32 v0, v94 offset:1056
	s_waitcnt vmcnt(26)
	ds_write_b32 v0, v95 offset:1320
	s_waitcnt vmcnt(25)
	ds_write_b32 v0, v96 offset:1584
	s_waitcnt vmcnt(24)
	ds_write_b32 v0, v97 offset:1848
	s_waitcnt vmcnt(23)
	ds_write_b32 v0, v98 offset:2112
	s_waitcnt vmcnt(22)
	ds_write_b32 v0, v99 offset:2376
	s_waitcnt vmcnt(21)
	ds_write_b32 v0, v100 offset:2640
	s_waitcnt vmcnt(20)
	ds_write_b32 v0, v101 offset:2904
	s_waitcnt vmcnt(19)
	ds_write_b32 v0, v102 offset:3168
	s_waitcnt vmcnt(18)
	ds_write_b32 v0, v103 offset:3432
	s_waitcnt vmcnt(17)
	ds_write_b32 v0, v104 offset:3696
	s_waitcnt vmcnt(16)
	ds_write_b32 v0, v105 offset:3960
	s_waitcnt vmcnt(15)
	ds_write_b32 v0, v110 offset:4224
	s_waitcnt vmcnt(14)
	ds_write_b32 v0, v111 offset:4488
	s_waitcnt vmcnt(13)
	ds_write_b32 v0, v112 offset:4752
	s_waitcnt vmcnt(12)
	ds_write_b32 v0, v113 offset:5016
	s_waitcnt vmcnt(11)
	ds_write_b32 v0, v114 offset:5280
	s_waitcnt vmcnt(10)
	ds_write_b32 v0, v115 offset:5544
	s_waitcnt vmcnt(9)
	ds_write_b32 v0, v116 offset:5808
	s_waitcnt vmcnt(8)
	ds_write_b32 v0, v117 offset:6072
	s_waitcnt vmcnt(7)
	ds_write_b32 v0, v118 offset:6336
	s_waitcnt vmcnt(6)
	ds_write_b32 v0, v119 offset:6600
	s_waitcnt vmcnt(5)
	ds_write_b32 v0, v120 offset:6864
	s_waitcnt vmcnt(4)
	ds_write_b32 v0, v121 offset:7128
	s_waitcnt vmcnt(3)
	ds_write_b32 v0, v122 offset:7392
	s_waitcnt vmcnt(2)
	ds_write_b32 v0, v123 offset:7656
	s_waitcnt vmcnt(1)
	ds_write_b32 v0, v124 offset:7920
	s_waitcnt vmcnt(0)
	ds_write_b32 v0, v125 offset:8184
	v_add_u32_e32 v0, 0x2100, v0
	s_waitcnt lgkmcnt(0)
	ds_read_b32 v0, v67
	ds_read_b32 v32, v67 offset:132
	s_lshl_b32 s1, s19, 1
	s_andn2_b32 s1, s1, 63
	s_add_i32 s62, s1, 0xffffa900
	s_waitcnt lgkmcnt(1)
	v_bfe_u32 v33, v0, 16, 1
	v_add3_u32 v0, v0, v33, s81
	s_waitcnt lgkmcnt(0)
	v_bfe_u32 v33, v32, 16, 1
	v_lshrrev_b32_e32 v0, 16, v0
	v_add3_u32 v32, v32, v33, s81
	v_and_or_b32 v32, v32, s46, v0
	ds_read_b32 v0, v67 offset:264
	ds_read_b32 v33, v67 offset:396
	v_lshl_add_u64 v[30:31], s[62:63], 1, v[8:9]
	s_waitcnt lgkmcnt(1)
	v_bfe_u32 v34, v0, 16, 1
	v_add3_u32 v0, v0, v34, s81
	s_waitcnt lgkmcnt(0)
	v_bfe_u32 v34, v33, 16, 1
	v_lshrrev_b32_e32 v0, 16, v0
	v_add3_u32 v33, v33, v34, s81
	v_and_or_b32 v33, v33, s46, v0
	ds_read_b32 v0, v67 offset:528
	ds_read_b32 v34, v67 offset:660
	s_waitcnt lgkmcnt(1)
	v_bfe_u32 v35, v0, 16, 1
	v_add3_u32 v0, v0, v35, s81
	s_waitcnt lgkmcnt(0)
	v_bfe_u32 v35, v34, 16, 1
	v_lshrrev_b32_e32 v0, 16, v0
	v_add3_u32 v34, v34, v35, s81
	v_and_or_b32 v34, v34, s46, v0
	ds_read_b32 v0, v67 offset:792
	ds_read_b32 v35, v67 offset:924
	s_waitcnt lgkmcnt(1)
	v_bfe_u32 v36, v0, 16, 1
	v_add3_u32 v0, v0, v36, s81
	s_waitcnt lgkmcnt(0)
	v_bfe_u32 v36, v35, 16, 1
	v_lshrrev_b32_e32 v0, 16, v0
	v_add3_u32 v35, v35, v36, s81
	v_and_or_b32 v35, v35, s46, v0
	v_or_b32_e32 v0, s0, v66
	v_mul_u32_u24_e32 v0, 0x1600, v0
	v_lshl_add_u64 v[36:37], v[30:31], 0, v[0:1]
	flat_store_dwordx4 v[36:37], v[32:35]
	ds_read_b32 v0, v67 offset:32
	ds_read_b32 v32, v67 offset:164
	s_waitcnt lgkmcnt(0)
	v_bfe_u32 v33, v0, 16, 1
	v_add3_u32 v0, v0, v33, s81
	v_bfe_u32 v33, v32, 16, 1
	v_lshrrev_b32_e32 v0, 16, v0
	v_add3_u32 v32, v32, v33, s81
	v_and_or_b32 v32, v32, s46, v0
	ds_read_b32 v0, v67 offset:296
	ds_read_b32 v33, v67 offset:428
	s_waitcnt lgkmcnt(0)
	v_bfe_u32 v34, v0, 16, 1
	v_add3_u32 v0, v0, v34, s81
	v_bfe_u32 v34, v33, 16, 1
	v_lshrrev_b32_e32 v0, 16, v0
	v_add3_u32 v33, v33, v34, s81
	v_and_or_b32 v33, v33, s46, v0
	ds_read_b32 v0, v67 offset:560
	ds_read_b32 v34, v67 offset:692
	s_waitcnt lgkmcnt(0)
	v_bfe_u32 v35, v0, 16, 1
	v_add3_u32 v0, v0, v35, s81
	v_bfe_u32 v35, v34, 16, 1
	v_lshrrev_b32_e32 v0, 16, v0
	v_add3_u32 v34, v34, v35, s81
	v_and_or_b32 v34, v34, s46, v0
	ds_read_b32 v0, v67 offset:824
	ds_read_b32 v35, v67 offset:956
	s_waitcnt lgkmcnt(0)
	v_bfe_u32 v36, v0, 16, 1
	v_add3_u32 v0, v0, v36, s81
	v_bfe_u32 v36, v35, 16, 1
	v_lshrrev_b32_e32 v0, 16, v0
	v_add3_u32 v35, v35, v36, s81
	v_and_or_b32 v35, v35, s46, v0
	v_or_b32_e32 v0, s0, v68
	v_mul_u32_u24_e32 v0, 0x1600, v0
	v_lshl_add_u64 v[36:37], v[30:31], 0, v[0:1]
	flat_store_dwordx4 v[36:37], v[32:35]
	ds_read_b32 v0, v67 offset:64
	ds_read_b32 v32, v67 offset:196
	s_waitcnt lgkmcnt(0)
	v_bfe_u32 v33, v0, 16, 1
	v_add3_u32 v0, v0, v33, s81
	v_bfe_u32 v33, v32, 16, 1
	v_lshrrev_b32_e32 v0, 16, v0
	v_add3_u32 v32, v32, v33, s81
	v_and_or_b32 v32, v32, s46, v0
	ds_read_b32 v0, v67 offset:328
	ds_read_b32 v33, v67 offset:460
	s_waitcnt lgkmcnt(0)
	v_bfe_u32 v34, v0, 16, 1
	v_add3_u32 v0, v0, v34, s81
	v_bfe_u32 v34, v33, 16, 1
	v_lshrrev_b32_e32 v0, 16, v0
	v_add3_u32 v33, v33, v34, s81
	v_and_or_b32 v33, v33, s46, v0
	ds_read_b32 v0, v67 offset:592
	ds_read_b32 v34, v67 offset:724
	s_waitcnt lgkmcnt(0)
	v_bfe_u32 v35, v0, 16, 1
	v_add3_u32 v0, v0, v35, s81
	v_bfe_u32 v35, v34, 16, 1
	v_lshrrev_b32_e32 v0, 16, v0
	v_add3_u32 v34, v34, v35, s81
	v_and_or_b32 v34, v34, s46, v0
	ds_read_b32 v0, v67 offset:856
	ds_read_b32 v35, v67 offset:988
	s_waitcnt lgkmcnt(0)
	v_bfe_u32 v36, v0, 16, 1
	v_add3_u32 v0, v0, v36, s81
	v_bfe_u32 v36, v35, 16, 1
	v_lshrrev_b32_e32 v0, 16, v0
	v_add3_u32 v35, v35, v36, s81
	v_and_or_b32 v35, v35, s46, v0
	v_or_b32_e32 v0, s0, v69
	v_mul_u32_u24_e32 v0, 0x1600, v0
	v_lshl_add_u64 v[36:37], v[30:31], 0, v[0:1]
	flat_store_dwordx4 v[36:37], v[32:35]
	ds_read_b32 v0, v67 offset:96
	ds_read_b32 v32, v67 offset:228
	s_waitcnt lgkmcnt(0)
	v_bfe_u32 v33, v0, 16, 1
	v_add3_u32 v0, v0, v33, s81
	v_bfe_u32 v33, v32, 16, 1
	v_lshrrev_b32_e32 v0, 16, v0
	v_add3_u32 v32, v32, v33, s81
	v_and_or_b32 v32, v32, s46, v0
	ds_read_b32 v0, v67 offset:360
	ds_read_b32 v33, v67 offset:492
	s_waitcnt lgkmcnt(0)
	v_bfe_u32 v34, v0, 16, 1
	v_add3_u32 v0, v0, v34, s81
	v_bfe_u32 v34, v33, 16, 1
	v_lshrrev_b32_e32 v0, 16, v0
	v_add3_u32 v33, v33, v34, s81
	v_and_or_b32 v33, v33, s46, v0
	ds_read_b32 v0, v67 offset:624
	ds_read_b32 v34, v67 offset:756
	s_waitcnt lgkmcnt(0)
	v_bfe_u32 v35, v0, 16, 1
	v_add3_u32 v0, v0, v35, s81
	v_bfe_u32 v35, v34, 16, 1
	v_lshrrev_b32_e32 v0, 16, v0
	v_add3_u32 v34, v34, v35, s81
	v_and_or_b32 v34, v34, s46, v0
	ds_read_b32 v0, v67 offset:888
	ds_read_b32 v35, v67 offset:1020
	s_waitcnt lgkmcnt(0)
	v_bfe_u32 v36, v0, 16, 1
	v_add3_u32 v0, v0, v36, s81
	v_bfe_u32 v36, v35, 16, 1
	v_lshrrev_b32_e32 v0, 16, v0
	v_add3_u32 v35, v35, v36, s81
	v_and_or_b32 v35, v35, s46, v0
	v_or_b32_e32 v0, s0, v70
	v_mul_u32_u24_e32 v0, 0x1600, v0
	v_lshl_add_u64 v[30:31], v[30:31], 0, v[0:1]
	flat_store_dwordx4 v[30:31], v[32:35]
	s_waitcnt lgkmcnt(0)
	s_mov_b64 s[0:1], 0

; template <bool MAPPED>
; __device__ __forceinline__ void transpose_item(const float* W, int K, int Nsrc, bf16_t* WT, const float* gk, LAS float* scr, int item, int nblk, int lane) {
;     ...
; #pragma unroll 8
;     for (int i = 0; i < 32; ++i) { const int kk = 2 * i + (lane >> 5); float v = (sc >= 0) ? W[(size_t)(k0 + kk) * Nsrc + sc] : 0.f; if (gk) v *= gk[k0 + kk]; scr[kk * 33 + (lane & 31)] = v; }
.LBB0_809:
	s_add_u32 s12, s12, 64
	s_addc_u32 s13, s13, 0
	s_mov_b64 s[4:5], 0x58000
	v_lshl_add_u64 v[34:35], v[34:35], 0, s[4:5]
	v_add_u32_e32 v0, 0x1080, v0
	s_cmpk_lg_i32 s12, 0x100
	s_cbranch_scc0 .LBB0_826
.LBB0_810:
	v_cndmask_b32_e64 v80, 0, 1, s[6:7]
	v_cmp_ne_u32_e64 s[10:11], 1, v80
	s_andn2_b64 vcc, exec, s[6:7]
	s_cbranch_vccnz .Ltq2n
	v_lshl_add_u64 v[80:81], v[62:63], 0, s[12:13]
	global_load_dword v110, v[80:81], off
	v_lshl_add_u64 v[80:81], v[56:57], 0, s[12:13]
	global_load_dword v111, v[80:81], off
	v_lshl_add_u64 v[80:81], v[52:53], 0, s[12:13]
	global_load_dword v112, v[80:81], off
	v_lshl_add_u64 v[80:81], v[48:49], 0, s[12:13]
	global_load_dword v113, v[80:81], off
	v_lshl_add_u64 v[80:81], v[44:45], 0, s[12:13]
	global_load_dword v114, v[80:81], off
	v_lshl_add_u64 v[80:81], v[40:41], 0, s[12:13]
	global_load_dword v115, v[80:81], off
	v_lshl_add_u64 v[80:81], v[36:37], 0, s[12:13]
	global_load_dword v116, v[80:81], off
	v_lshl_add_u64 v[80:81], v[30:31], 0, s[12:13]
	global_load_dword v117, v[80:81], off
	v_lshl_add_u64 v[80:81], v[62:63], 0, s[12:13]
	global_load_dword v118, v[80:81], off offset:64
	v_lshl_add_u64 v[80:81], v[56:57], 0, s[12:13]
	global_load_dword v119, v[80:81], off offset:64
	v_lshl_add_u64 v[80:81], v[52:53], 0, s[12:13]
	global_load_dword v120, v[80:81], off offset:64
	v_lshl_add_u64 v[80:81], v[48:49], 0, s[12:13]
	global_load_dword v121, v[80:81], off offset:64
	v_lshl_add_u64 v[80:81], v[44:45], 0, s[12:13]
	global_load_dword v122, v[80:81], off offset:64
	v_lshl_add_u64 v[80:81], v[40:41], 0, s[12:13]
	global_load_dword v123, v[80:81], off offset:64
	v_lshl_add_u64 v[80:81], v[36:37], 0, s[12:13]
	global_load_dword v124, v[80:81], off offset:64
	v_lshl_add_u64 v[80:81], v[30:31], 0, s[12:13]
	global_load_dword v125, v[80:81], off offset:64
	v_lshl_add_u64 v[80:81], v[34:35], 0, v[60:61]
	global_load_dword v90, v[80:81], off
	v_lshl_add_u64 v[80:81], v[34:35], 0, v[58:59]
	global_load_dword v91, v[80:81], off
	v_lshl_add_u64 v[80:81], v[34:35], 0, v[54:55]
	global_load_dword v92, v[80:81], off
	v_lshl_add_u64 v[80:81], v[34:35], 0, v[50:51]
	global_load_dword v93, v[80:81], off
	v_lshl_add_u64 v[80:81], v[34:35], 0, v[46:47]
	global_load_dword v94, v[80:81], off
	v_lshl_add_u64 v[80:81], v[34:35], 0, v[42:43]
	global_load_dword v95, v[80:81], off
	v_lshl_add_u64 v[80:81], v[34:35], 0, v[38:39]
	global_load_dword v96, v[80:81], off
	v_lshl_add_u64 v[80:81], v[34:35], 0, v[32:33]
	global_load_dword v97, v[80:81], off
	s_add_u32 s12, s12, 64
	s_addc_u32 s13, s13, 0
	s_mov_b64 s[4:5], 0x58000
	v_lshl_add_u64 v[34:35], v[34:35], 0, s[4:5]
	v_lshl_add_u64 v[80:81], v[34:35], 0, v[60:61]
	global_load_dword v98, v[80:81], off
	v_lshl_add_u64 v[80:81], v[34:35], 0, v[58:59]
	global_load_dword v99, v[80:81], off
	v_lshl_add_u64 v[80:81], v[34:35], 0, v[54:55]
	global_load_dword v100, v[80:81], off
	v_lshl_add_u64 v[80:81], v[34:35], 0, v[50:51]
	global_load_dword v101, v[80:81], off
	v_lshl_add_u64 v[80:81], v[34:35], 0, v[46:47]
	global_load_dword v102, v[80:81], off
	v_lshl_add_u64 v[80:81], v[34:35], 0, v[42:43]
	global_load_dword v103, v[80:81], off
	v_lshl_add_u64 v[80:81], v[34:35], 0, v[38:39]
	global_load_dword v104, v[80:81], off
	v_lshl_add_u64 v[80:81], v[34:35], 0, v[32:33]
	global_load_dword v105, v[80:81], off
	s_waitcnt vmcnt(15)
	v_mul_f32_e32 v90, v90, v110
	ds_write_b32 v0, v90
	s_waitcnt vmcnt(14)
	v_mul_f32_e32 v91, v91, v111
	ds_write_b32 v0, v91 offset:264
	s_waitcnt vmcnt(13)
	v_mul_f32_e32 v92, v92, v112
	ds_write_b32 v0, v92 offset:528
	s_waitcnt vmcnt(12)
	v_mul_f32_e32 v93, v93, v113
	ds_write_b32 v0, v93 offset:792
	s_waitcnt vmcnt(11)
	v_mul_f32_e32 v94, v94, v114
	ds_write_b32 v0, v94 offset:1056
	s_waitcnt vmcnt(10)
	v_mul_f32_e32 v95, v95, v115
	ds_write_b32 v0, v95 offset:1320
	s_waitcnt vmcnt(9)
	v_mul_f32_e32 v96, v96, v116
	ds_write_b32 v0, v96 offset:1584
	s_waitcnt vmcnt(8)
	v_mul_f32_e32 v97, v97, v117
	ds_write_b32 v0, v97 offset:1848
	s_waitcnt vmcnt(7)
	v_mul_f32_e32 v98, v98, v118
	ds_write_b32 v0, v98 offset:2112
	s_waitcnt vmcnt(6)
	v_mul_f32_e32 v99, v99, v119
	ds_write_b32 v0, v99 offset:2376
	s_waitcnt vmcnt(5)
	v_mul_f32_e32 v100, v100, v120
	ds_write_b32 v0, v100 offset:2640
	s_waitcnt vmcnt(4)
	v_mul_f32_e32 v101, v101, v121
	ds_write_b32 v0, v101 offset:2904
	s_waitcnt vmcnt(3)
	v_mul_f32_e32 v102, v102, v122
	ds_write_b32 v0, v102 offset:3168
	s_waitcnt vmcnt(2)
	v_mul_f32_e32 v103, v103, v123
	ds_write_b32 v0, v103 offset:3432
	s_waitcnt vmcnt(1)
	v_mul_f32_e32 v104, v104, v124
	ds_write_b32 v0, v104 offset:3696
	s_waitcnt vmcnt(0)
	v_mul_f32_e32 v105, v105, v125
	ds_write_b32 v0, v105 offset:3960
	s_branch .LBB0_809
; template <bool MAPPED>
; __device__ __forceinline__ void transpose_item(const float* W, int K, int Nsrc, bf16_t* WT, const float* gk, LAS float* scr, int item, int nblk, int lane) {
;     ...
; #pragma unroll 8
;     for (int i = 0; i < 32; ++i) { const int kk = 2 * i + (lane >> 5); float v = (sc >= 0) ? W[(size_t)(k0 + kk) * Nsrc + sc] : 0.f; if (gk) v *= gk[k0 + kk]; scr[kk * 33 + (lane & 31)] = v; }
.Ltq2n:
	v_lshl_add_u64 v[80:81], v[34:35], 0, v[60:61]
	global_load_dword v90, v[80:81], off
	v_lshl_add_u64 v[80:81], v[34:35], 0, v[58:59]
	global_load_dword v91, v[80:81], off
	v_lshl_add_u64 v[80:81], v[34:35], 0, v[54:55]
	global_load_dword v92, v[80:81], off
	v_lshl_add_u64 v[80:81], v[34:35], 0, v[50:51]
	global_load_dword v93, v[80:81], off
	v_lshl_add_u64 v[80:81], v[34:35], 0, v[46:47]
	global_load_dword v94, v[80:81], off
	v_lshl_add_u64 v[80:81], v[34:35], 0, v[42:43]
	global_load_dword v95, v[80:81], off
	v_lshl_add_u64 v[80:81], v[34:35], 0, v[38:39]
	global_load_dword v96, v[80:81], off
	v_lshl_add_u64 v[80:81], v[34:35], 0, v[32:33]
	global_load_dword v97, v[80:81], off
	s_add_u32 s12, s12, 64
	s_addc_u32 s13, s13, 0
	s_mov_b64 s[4:5], 0x58000
	v_lshl_add_u64 v[34:35], v[34:35], 0, s[4:5]
	v_lshl_add_u64 v[80:81], v[34:35], 0, v[60:61]
	global_load_dword v98, v[80:81], off
	v_lshl_add_u64 v[80:81], v[34:35], 0, v[58:59]
	global_load_dword v99, v[80:81], off
	v_lshl_add_u64 v[80:81], v[34:35], 0, v[54:55]
	global_load_dword v100, v[80:81], off
	v_lshl_add_u64 v[80:81], v[34:35], 0, v[50:51]
	global_load_dword v101, v[80:81], off
	v_lshl_add_u64 v[80:81], v[34:35], 0, v[46:47]
	global_load_dword v102, v[80:81], off
	v_lshl_add_u64 v[80:81], v[34:35], 0, v[42:43]
	global_load_dword v103, v[80:81], off
	v_lshl_add_u64 v[80:81], v[34:35], 0, v[38:39]
	global_load_dword v104, v[80:81], off
	v_lshl_add_u64 v[80:81], v[34:35], 0, v[32:33]
	global_load_dword v105, v[80:81], off
	s_waitcnt vmcnt(15)
	ds_write_b32 v0, v90
	s_waitcnt vmcnt(14)
	ds_write_b32 v0, v91 offset:264
	s_waitcnt vmcnt(13)
	ds_write_b32 v0, v92 offset:528
	s_waitcnt vmcnt(12)
	ds_write_b32 v0, v93 offset:792
	s_waitcnt vmcnt(11)
	ds_write_b32 v0, v94 offset:1056
	s_waitcnt vmcnt(10)
	ds_write_b32 v0, v95 offset:1320
	s_waitcnt vmcnt(9)
	ds_write_b32 v0, v96 offset:1584
	s_waitcnt vmcnt(8)
	ds_write_b32 v0, v97 offset:1848
	s_waitcnt vmcnt(7)
	ds_write_b32 v0, v98 offset:2112
	s_waitcnt vmcnt(6)
	ds_write_b32 v0, v99 offset:2376
	s_waitcnt vmcnt(5)
	ds_write_b32 v0, v100 offset:2640
	s_waitcnt vmcnt(4)
	ds_write_b32 v0, v101 offset:2904
	s_waitcnt vmcnt(3)
	ds_write_b32 v0, v102 offset:3168
	s_waitcnt vmcnt(2)
	ds_write_b32 v0, v103 offset:3432
	s_waitcnt vmcnt(1)
	ds_write_b32 v0, v104 offset:3696
	s_waitcnt vmcnt(0)
	ds_write_b32 v0, v105 offset:3960
	s_branch .LBB0_809

; #define LAS __attribute__((address_space(3)))
; __device__ __forceinline__ unsigned pk2(float lo, float hi) { return f2bf(lo) | (f2bf(hi) << 16); }
; template <bool MAPPED>
; __device__ __forceinline__ void transpose_item(const float* W, int K, int Nsrc, bf16_t* WT, const float* gk, LAS float* scr, int item, int nblk, int lane) {
;     ...
; #pragma unroll 8
;     for (int i = 0; i < 32; ++i) { const int kk = 2 * i + (lane >> 5); float v = (sc >= 0) ? W[(size_t)(k0 + kk) * Nsrc + sc] : 0.f; if (gk) v *= gk[k0 + kk]; scr[kk * 33 + (lane & 31)] = v; }
;     asm volatile("s_waitcnt lgkmcnt(0)" ::: "memory");
;     const int c = lane & 7;
; #pragma unroll
;     for (int j = 0; j < 4; ++j) { const int n = (lane >> 3) + 8 * j; const LAS float* s = scr + (8 * c) * 33 + n;
;         u32x4 o; o.x = pk2(s[0 * 33], s[1 * 33]); o.y = pk2(s[2 * 33], s[3 * 33]); o.z = pk2(s[4 * 33], s[5 * 33]); o.w = pk2(s[6 * 33], s[7 * 33]);
.LBB0_830:
	v_lshl_add_u64 v[46:47], v[44:45], 0, s[0:1]
	global_load_dword v90, v[46:47], off
	v_lshl_add_u64 v[46:47], v[42:43], 0, s[0:1]
	global_load_dword v91, v[46:47], off
	v_lshl_add_u64 v[46:47], v[40:41], 0, s[0:1]
	global_load_dword v92, v[46:47], off
	v_lshl_add_u64 v[46:47], v[38:39], 0, s[0:1]
	global_load_dword v93, v[46:47], off
	v_lshl_add_u64 v[46:47], v[36:37], 0, s[0:1]
	global_load_dword v94, v[46:47], off
	v_lshl_add_u64 v[46:47], v[34:35], 0, s[0:1]
	global_load_dword v95, v[46:47], off
	v_lshl_add_u64 v[46:47], v[32:33], 0, s[0:1]
	global_load_dword v96, v[46:47], off
	v_lshl_add_u64 v[46:47], v[30:31], 0, s[0:1]
	s_add_u32 s0, s0, 0x10000
	s_addc_u32 s1, s1, 0
	global_load_dword v97, v[46:47], off
	v_lshl_add_u64 v[46:47], v[44:45], 0, s[0:1]
	global_load_dword v98, v[46:47], off
	v_lshl_add_u64 v[46:47], v[42:43], 0, s[0:1]
	global_load_dword v99, v[46:47], off
	v_lshl_add_u64 v[46:47], v[40:41], 0, s[0:1]
	global_load_dword v100, v[46:47], off
	v_lshl_add_u64 v[46:47], v[38:39], 0, s[0:1]
	global_load_dword v101, v[46:47], off
	v_lshl_add_u64 v[46:47], v[36:37], 0, s[0:1]
	global_load_dword v102, v[46:47], off
	v_lshl_add_u64 v[46:47], v[34:35], 0, s[0:1]
	global_load_dword v103, v[46:47], off
	v_lshl_add_u64 v[46:47], v[32:33], 0, s[0:1]
	global_load_dword v104, v[46:47], off
	v_lshl_add_u64 v[46:47], v[30:31], 0, s[0:1]
	s_add_u32 s0, s0, 0x10000
	s_addc_u32 s1, s1, 0
	global_load_dword v105, v[46:47], off
	v_lshl_add_u64 v[46:47], v[44:45], 0, s[0:1]
	global_load_dword v110, v[46:47], off
	v_lshl_add_u64 v[46:47], v[42:43], 0, s[0:1]
	global_load_dword v111, v[46:47], off
	v_lshl_add_u64 v[46:47], v[40:41], 0, s[0:1]
	global_load_dword v112, v[46:47], off
	v_lshl_add_u64 v[46:47], v[38:39], 0, s[0:1]
	global_load_dword v113, v[46:47], off
	v_lshl_add_u64 v[46:47], v[36:37], 0, s[0:1]
	global_load_dword v114, v[46:47], off
	v_lshl_add_u64 v[46:47], v[34:35], 0, s[0:1]
	global_load_dword v115, v[46:47], off
	v_lshl_add_u64 v[46:47], v[32:33], 0, s[0:1]
	global_load_dword v116, v[46:47], off
	v_lshl_add_u64 v[46:47], v[30:31], 0, s[0:1]
	s_add_u32 s0, s0, 0x10000
	s_addc_u32 s1, s1, 0
	global_load_dword v117, v[46:47], off
	v_lshl_add_u64 v[46:47], v[44:45], 0, s[0:1]
	global_load_dword v118, v[46:47], off
	v_lshl_add_u64 v[46:47], v[42:43], 0, s[0:1]
	global_load_dword v119, v[46:47], off
	v_lshl_add_u64 v[46:47], v[40:41], 0, s[0:1]
	global_load_dword v120, v[46:47], off
	v_lshl_add_u64 v[46:47], v[38:39], 0, s[0:1]
	global_load_dword v121, v[46:47], off
	v_lshl_add_u64 v[46:47], v[36:37], 0, s[0:1]
	global_load_dword v122, v[46:47], off
	v_lshl_add_u64 v[46:47], v[34:35], 0, s[0:1]
	global_load_dword v123, v[46:47], off
	v_lshl_add_u64 v[46:47], v[32:33], 0, s[0:1]
	global_load_dword v124, v[46:47], off
	v_lshl_add_u64 v[46:47], v[30:31], 0, s[0:1]
	s_add_u32 s0, s0, 0x10000
	s_addc_u32 s1, s1, 0
	global_load_dword v125, v[46:47], off
	s_waitcnt vmcnt(31)
	ds_write_b32 v0, v90
	s_waitcnt vmcnt(30)
	ds_write_b32 v0, v91 offset:264
	s_waitcnt vmcnt(29)
	ds_write_b32 v0, v92 offset:528
	s_waitcnt vmcnt(28)
	ds_write_b32 v0, v93 offset:792
	s_waitcnt vmcnt(27)
	ds_write_b32 v0, v94 offset:1056
	s_waitcnt vmcnt(26)
	ds_write_b32 v0, v95 offset:1320
	s_waitcnt vmcnt(25)
	ds_write_b32 v0, v96 offset:1584
	s_waitcnt vmcnt(24)
	ds_write_b32 v0, v97 offset:1848
	s_waitcnt vmcnt(23)
	ds_write_b32 v0, v98 offset:2112
	s_waitcnt vmcnt(22)
	ds_write_b32 v0, v99 offset:2376
	s_waitcnt vmcnt(21)
	ds_write_b32 v0, v100 offset:2640
	s_waitcnt vmcnt(20)
	ds_write_b32 v0, v101 offset:2904
	s_waitcnt vmcnt(19)
	ds_write_b32 v0, v102 offset:3168
	s_waitcnt vmcnt(18)
	ds_write_b32 v0, v103 offset:3432
	s_waitcnt vmcnt(17)
	ds_write_b32 v0, v104 offset:3696
	s_waitcnt vmcnt(16)
	ds_write_b32 v0, v105 offset:3960
	s_waitcnt vmcnt(15)
	ds_write_b32 v0, v110 offset:4224
	s_waitcnt vmcnt(14)
	ds_write_b32 v0, v111 offset:4488
	s_waitcnt vmcnt(13)
	ds_write_b32 v0, v112 offset:4752
	s_waitcnt vmcnt(12)
	ds_write_b32 v0, v113 offset:5016
	s_waitcnt vmcnt(11)
	ds_write_b32 v0, v114 offset:5280
	s_waitcnt vmcnt(10)
	ds_write_b32 v0, v115 offset:5544
	s_waitcnt vmcnt(9)
	ds_write_b32 v0, v116 offset:5808
	s_waitcnt vmcnt(8)
	ds_write_b32 v0, v117 offset:6072
	s_waitcnt vmcnt(7)
	ds_write_b32 v0, v118 offset:6336
	s_waitcnt vmcnt(6)
	ds_write_b32 v0, v119 offset:6600
	s_waitcnt vmcnt(5)
	ds_write_b32 v0, v120 offset:6864
	s_waitcnt vmcnt(4)
	ds_write_b32 v0, v121 offset:7128
	s_waitcnt vmcnt(3)
	ds_write_b32 v0, v122 offset:7392
	s_waitcnt vmcnt(2)
	ds_write_b32 v0, v123 offset:7656
	s_waitcnt vmcnt(1)
	ds_write_b32 v0, v124 offset:7920
	s_waitcnt vmcnt(0)
	ds_write_b32 v0, v125 offset:8184
	v_add_u32_e32 v0, 0x2100, v0
	s_waitcnt lgkmcnt(0)
	ds_read_b32 v0, v67
	ds_read_b32 v32, v67 offset:132
	s_lshl_b32 s0, s19, 1
	s_add_i32 s0, s0, 0x1c300
	s_and_b32 s1, s0, 0x1ffc0
	s_waitcnt lgkmcnt(1)
; #define LAS __attribute__((address_space(3)))
; __device__ __forceinline__ unsigned pk2(float lo, float hi) { return f2bf(lo) | (f2bf(hi) << 16); }
; template <bool MAPPED>
; __device__ __forceinline__ void transpose_item(const float* W, int K, int Nsrc, bf16_t* WT, const float* gk, LAS float* scr, int item, int nblk, int lane) {
;     ...
;     asm volatile("s_waitcnt lgkmcnt(0)" ::: "memory");
;     const int c = lane & 7;
; #pragma unroll
;     for (int j = 0; j < 4; ++j) { const int n = (lane >> 3) + 8 * j; const LAS float* s = scr + (8 * c) * 33 + n;
;         u32x4 o; o.x = pk2(s[0 * 33], s[1 * 33]); o.y = pk2(s[2 * 33], s[3 * 33]); o.z = pk2(s[4 * 33], s[5 * 33]); o.w = pk2(s[6 * 33], s[7 * 33]);
;         *(u32x4*)(WT + (size_t)(j0 + n) * K + k0 + 8 * c) = o; }
;     asm volatile("s_waitcnt lgkmcnt(0)" ::: "memory");
	v_bfe_u32 v33, v0, 16, 1
	v_add3_u32 v0, v0, v33, s81
	s_waitcnt lgkmcnt(0)
	v_bfe_u32 v33, v32, 16, 1
	v_lshrrev_b32_e32 v0, 16, v0
	v_add3_u32 v32, v32, v33, s81
	v_and_or_b32 v32, v32, s46, v0
	ds_read_b32 v0, v67 offset:264
	ds_read_b32 v33, v67 offset:396
	s_lshl_b32 s0, s19, 5
	s_and_b32 s0, s0, 0x3e0
	s_lshl_b32 s62, s1, 1
	s_waitcnt lgkmcnt(1)
	v_bfe_u32 v34, v0, 16, 1
	v_add3_u32 v0, v0, v34, s81
	s_waitcnt lgkmcnt(0)
	v_bfe_u32 v34, v33, 16, 1
	v_lshrrev_b32_e32 v0, 16, v0
	v_add3_u32 v33, v33, v34, s81
	v_and_or_b32 v33, v33, s46, v0
	ds_read_b32 v0, v67 offset:528
	ds_read_b32 v34, v67 offset:660
	v_lshl_add_u64 v[30:31], v[12:13], 0, s[62:63]
	s_waitcnt lgkmcnt(1)
	v_bfe_u32 v35, v0, 16, 1
	v_add3_u32 v0, v0, v35, s81
	s_waitcnt lgkmcnt(0)
	v_bfe_u32 v35, v34, 16, 1
	v_lshrrev_b32_e32 v0, 16, v0
	v_add3_u32 v34, v34, v35, s81
	v_and_or_b32 v34, v34, s46, v0
	ds_read_b32 v0, v67 offset:792
	ds_read_b32 v35, v67 offset:924
	s_waitcnt lgkmcnt(1)
	v_bfe_u32 v36, v0, 16, 1
	v_add3_u32 v0, v0, v36, s81
	s_waitcnt lgkmcnt(0)
	v_bfe_u32 v36, v35, 16, 1
	v_lshrrev_b32_e32 v0, 16, v0
	v_add3_u32 v35, v35, v36, s81
	v_and_or_b32 v35, v35, s46, v0
	v_or_b32_e32 v0, s0, v66
	v_lshlrev_b32_e32 v0, 11, v0
	v_lshl_add_u64 v[36:37], v[30:31], 0, v[0:1]
	flat_store_dwordx4 v[36:37], v[32:35]
	ds_read_b32 v0, v67 offset:32
	ds_read_b32 v32, v67 offset:164
	s_waitcnt lgkmcnt(0)
	v_bfe_u32 v33, v0, 16, 1
	v_add3_u32 v0, v0, v33, s81
	v_bfe_u32 v33, v32, 16, 1
	v_lshrrev_b32_e32 v0, 16, v0
	v_add3_u32 v32, v32, v33, s81
	v_and_or_b32 v32, v32, s46, v0
	ds_read_b32 v0, v67 offset:296
	ds_read_b32 v33, v67 offset:428
	s_waitcnt lgkmcnt(0)
	v_bfe_u32 v34, v0, 16, 1
	v_add3_u32 v0, v0, v34, s81
	v_bfe_u32 v34, v33, 16, 1
	v_lshrrev_b32_e32 v0, 16, v0
	v_add3_u32 v33, v33, v34, s81
	v_and_or_b32 v33, v33, s46, v0
	ds_read_b32 v0, v67 offset:560
	ds_read_b32 v34, v67 offset:692
	s_waitcnt lgkmcnt(0)
	v_bfe_u32 v35, v0, 16, 1
	v_add3_u32 v0, v0, v35, s81
	v_bfe_u32 v35, v34, 16, 1
	v_lshrrev_b32_e32 v0, 16, v0
	v_add3_u32 v34, v34, v35, s81
	v_and_or_b32 v34, v34, s46, v0
	ds_read_b32 v0, v67 offset:824
	ds_read_b32 v35, v67 offset:956
	s_waitcnt lgkmcnt(0)
	v_bfe_u32 v36, v0, 16, 1
	v_add3_u32 v0, v0, v36, s81
	v_bfe_u32 v36, v35, 16, 1
	v_lshrrev_b32_e32 v0, 16, v0
	v_add3_u32 v35, v35, v36, s81
	v_and_or_b32 v35, v35, s46, v0
	v_or_b32_e32 v0, s0, v68
	v_lshlrev_b32_e32 v0, 11, v0
	v_lshl_add_u64 v[36:37], v[30:31], 0, v[0:1]
	flat_store_dwordx4 v[36:37], v[32:35]
	ds_read_b32 v0, v67 offset:64
	ds_read_b32 v32, v67 offset:196
	s_waitcnt lgkmcnt(0)
	v_bfe_u32 v33, v0, 16, 1
	v_add3_u32 v0, v0, v33, s81
	v_bfe_u32 v33, v32, 16, 1
	v_lshrrev_b32_e32 v0, 16, v0
	v_add3_u32 v32, v32, v33, s81
	v_and_or_b32 v32, v32, s46, v0
	ds_read_b32 v0, v67 offset:328
	ds_read_b32 v33, v67 offset:460
	s_waitcnt lgkmcnt(0)
	v_bfe_u32 v34, v0, 16, 1
	v_add3_u32 v0, v0, v34, s81
	v_bfe_u32 v34, v33, 16, 1
	v_lshrrev_b32_e32 v0, 16, v0
	v_add3_u32 v33, v33, v34, s81
	v_and_or_b32 v33, v33, s46, v0
	ds_read_b32 v0, v67 offset:592
	ds_read_b32 v34, v67 offset:724
	s_waitcnt lgkmcnt(0)
	v_bfe_u32 v35, v0, 16, 1
	v_add3_u32 v0, v0, v35, s81
	v_bfe_u32 v35, v34, 16, 1
	v_lshrrev_b32_e32 v0, 16, v0
	v_add3_u32 v34, v34, v35, s81
	v_and_or_b32 v34, v34, s46, v0
	ds_read_b32 v0, v67 offset:856
	ds_read_b32 v35, v67 offset:988
	s_waitcnt lgkmcnt(0)
	v_bfe_u32 v36, v0, 16, 1
	v_add3_u32 v0, v0, v36, s81
	v_bfe_u32 v36, v35, 16, 1
	v_lshrrev_b32_e32 v0, 16, v0
	v_add3_u32 v35, v35, v36, s81
	v_and_or_b32 v35, v35, s46, v0
	v_or_b32_e32 v0, s0, v69
	v_lshlrev_b32_e32 v0, 11, v0
	v_lshl_add_u64 v[36:37], v[30:31], 0, v[0:1]
	flat_store_dwordx4 v[36:37], v[32:35]
	ds_read_b32 v0, v67 offset:96
	ds_read_b32 v32, v67 offset:228
	s_waitcnt lgkmcnt(0)
	v_bfe_u32 v33, v0, 16, 1
	v_add3_u32 v0, v0, v33, s81
	v_bfe_u32 v33, v32, 16, 1
	v_lshrrev_b32_e32 v0, 16, v0
	v_add3_u32 v32, v32, v33, s81
	v_and_or_b32 v32, v32, s46, v0
	ds_read_b32 v0, v67 offset:360
	ds_read_b32 v33, v67 offset:492
	s_waitcnt lgkmcnt(0)
	v_bfe_u32 v34, v0, 16, 1
	v_add3_u32 v0, v0, v34, s81
	v_bfe_u32 v34, v33, 16, 1
	v_lshrrev_b32_e32 v0, 16, v0
	v_add3_u32 v33, v33, v34, s81
	v_and_or_b32 v33, v33, s46, v0
	ds_read_b32 v0, v67 offset:624
	ds_read_b32 v34, v67 offset:756
	s_waitcnt lgkmcnt(0)
	v_bfe_u32 v35, v0, 16, 1
	v_add3_u32 v0, v0, v35, s81
	v_bfe_u32 v35, v34, 16, 1
	v_lshrrev_b32_e32 v0, 16, v0
	v_add3_u32 v34, v34, v35, s81
	v_and_or_b32 v34, v34, s46, v0
	ds_read_b32 v0, v67 offset:888
	ds_read_b32 v35, v67 offset:1020
	s_waitcnt lgkmcnt(0)
	v_bfe_u32 v36, v0, 16, 1
	v_add3_u32 v0, v0, v36, s81
	v_bfe_u32 v36, v35, 16, 1
	v_lshrrev_b32_e32 v0, 16, v0
	v_add3_u32 v35, v35, v36, s81
	v_and_or_b32 v35, v35, s46, v0
	v_or_b32_e32 v0, s0, v70
	v_lshlrev_b32_e32 v0, 11, v0
	v_lshl_add_u64 v[30:31], v[30:31], 0, v[0:1]
	flat_store_dwordx4 v[30:31], v[32:35]
	s_waitcnt lgkmcnt(0)

; template <bool MAPPED>
; __device__ __forceinline__ void transpose_item(const float* W, int K, int Nsrc, bf16_t* WT, const float* gk, LAS float* scr, int item, int nblk, int lane) {
;     ...
; #pragma unroll 8
;     for (int i = 0; i < 32; ++i) { const int kk = 2 * i + (lane >> 5); float v = (sc >= 0) ? W[(size_t)(k0 + kk) * Nsrc + sc] : 0.f; if (gk) v *= gk[k0 + kk]; scr[kk * 33 + (lane & 31)] = v; }
; __device__ __forceinline__ void weights_phase(Frame& F, int layer, int part, int nparts, int gw, int NGW) {
;     ...
;         if (r < 3 * N_BR) { const int n = r / N_BR; transpose_item<false>(w_br + (size_t)n * D * D, D, D, WSP(bf16_t, OFF_WBR + layer * W_LAYER) + (size_t)n * D * D, nullptr, scr, r % N_BR, 32, F.lane); continue; } r -= 3 * N_BR;
.LBB0_835:
	v_lshl_add_u64 v[46:47], v[44:45], 0, s[0:1]
	global_load_dword v90, v[46:47], off
	v_lshl_add_u64 v[46:47], v[42:43], 0, s[0:1]
	global_load_dword v91, v[46:47], off
	v_lshl_add_u64 v[46:47], v[40:41], 0, s[0:1]
	global_load_dword v92, v[46:47], off
	v_lshl_add_u64 v[46:47], v[38:39], 0, s[0:1]
	global_load_dword v93, v[46:47], off
	v_lshl_add_u64 v[46:47], v[36:37], 0, s[0:1]
	global_load_dword v94, v[46:47], off
	v_lshl_add_u64 v[46:47], v[34:35], 0, s[0:1]
	global_load_dword v95, v[46:47], off
	v_lshl_add_u64 v[46:47], v[32:33], 0, s[0:1]
	global_load_dword v96, v[46:47], off
	v_lshl_add_u64 v[46:47], v[30:31], 0, s[0:1]
	s_add_u32 s0, s0, 0x10000
	s_addc_u32 s1, s1, 0
	global_load_dword v97, v[46:47], off
	v_lshl_add_u64 v[46:47], v[44:45], 0, s[0:1]
	global_load_dword v98, v[46:47], off
	v_lshl_add_u64 v[46:47], v[42:43], 0, s[0:1]
	global_load_dword v99, v[46:47], off
	v_lshl_add_u64 v[46:47], v[40:41], 0, s[0:1]
	global_load_dword v100, v[46:47], off
	v_lshl_add_u64 v[46:47], v[38:39], 0, s[0:1]
	global_load_dword v101, v[46:47], off
	v_lshl_add_u64 v[46:47], v[36:37], 0, s[0:1]
	global_load_dword v102, v[46:47], off
	v_lshl_add_u64 v[46:47], v[34:35], 0, s[0:1]
	global_load_dword v103, v[46:47], off
	v_lshl_add_u64 v[46:47], v[32:33], 0, s[0:1]
	global_load_dword v104, v[46:47], off
	v_lshl_add_u64 v[46:47], v[30:31], 0, s[0:1]
	s_add_u32 s0, s0, 0x10000
	s_addc_u32 s1, s1, 0
	global_load_dword v105, v[46:47], off
	v_lshl_add_u64 v[46:47], v[44:45], 0, s[0:1]
	global_load_dword v110, v[46:47], off
	v_lshl_add_u64 v[46:47], v[42:43], 0, s[0:1]
	global_load_dword v111, v[46:47], off
	v_lshl_add_u64 v[46:47], v[40:41], 0, s[0:1]
	global_load_dword v112, v[46:47], off
	v_lshl_add_u64 v[46:47], v[38:39], 0, s[0:1]
	global_load_dword v113, v[46:47], off
	v_lshl_add_u64 v[46:47], v[36:37], 0, s[0:1]
	global_load_dword v114, v[46:47], off
	v_lshl_add_u64 v[46:47], v[34:35], 0, s[0:1]
	global_load_dword v115, v[46:47], off
	v_lshl_add_u64 v[46:47], v[32:33], 0, s[0:1]
	global_load_dword v116, v[46:47], off
	v_lshl_add_u64 v[46:47], v[30:31], 0, s[0:1]
	s_add_u32 s0, s0, 0x10000
	s_addc_u32 s1, s1, 0
	global_load_dword v117, v[46:47], off
	v_lshl_add_u64 v[46:47], v[44:45], 0, s[0:1]
	global_load_dword v118, v[46:47], off
	v_lshl_add_u64 v[46:47], v[42:43], 0, s[0:1]
	global_load_dword v119, v[46:47], off
	v_lshl_add_u64 v[46:47], v[40:41], 0, s[0:1]
	global_load_dword v120, v[46:47], off
	v_lshl_add_u64 v[46:47], v[38:39], 0, s[0:1]
	global_load_dword v121, v[46:47], off
	v_lshl_add_u64 v[46:47], v[36:37], 0, s[0:1]
	global_load_dword v122, v[46:47], off
	v_lshl_add_u64 v[46:47], v[34:35], 0, s[0:1]
	global_load_dword v123, v[46:47], off
	v_lshl_add_u64 v[46:47], v[32:33], 0, s[0:1]
	global_load_dword v124, v[46:47], off
	v_lshl_add_u64 v[46:47], v[30:31], 0, s[0:1]
	s_add_u32 s0, s0, 0x10000
	s_addc_u32 s1, s1, 0
	global_load_dword v125, v[46:47], off
	s_waitcnt vmcnt(31)
	ds_write_b32 v0, v90
	s_waitcnt vmcnt(30)
	ds_write_b32 v0, v91 offset:264
	s_waitcnt vmcnt(29)
	ds_write_b32 v0, v92 offset:528
	s_waitcnt vmcnt(28)
	ds_write_b32 v0, v93 offset:792
	s_waitcnt vmcnt(27)
	ds_write_b32 v0, v94 offset:1056
	s_waitcnt vmcnt(26)
	ds_write_b32 v0, v95 offset:1320
	s_waitcnt vmcnt(25)
	ds_write_b32 v0, v96 offset:1584
	s_waitcnt vmcnt(24)
	ds_write_b32 v0, v97 offset:1848
	s_waitcnt vmcnt(23)
	ds_write_b32 v0, v98 offset:2112
	s_waitcnt vmcnt(22)
	ds_write_b32 v0, v99 offset:2376
	s_waitcnt vmcnt(21)
	ds_write_b32 v0, v100 offset:2640
	s_waitcnt vmcnt(20)
	ds_write_b32 v0, v101 offset:2904
	s_waitcnt vmcnt(19)
	ds_write_b32 v0, v102 offset:3168
	s_waitcnt vmcnt(18)
	ds_write_b32 v0, v103 offset:3432
	s_waitcnt vmcnt(17)
	ds_write_b32 v0, v104 offset:3696
	s_waitcnt vmcnt(16)
	ds_write_b32 v0, v105 offset:3960
	s_waitcnt vmcnt(15)
	ds_write_b32 v0, v110 offset:4224
	s_waitcnt vmcnt(14)
	ds_write_b32 v0, v111 offset:4488
	s_waitcnt vmcnt(13)
	ds_write_b32 v0, v112 offset:4752
	s_waitcnt vmcnt(12)
	ds_write_b32 v0, v113 offset:5016
	s_waitcnt vmcnt(11)
	ds_write_b32 v0, v114 offset:5280
	s_waitcnt vmcnt(10)
	ds_write_b32 v0, v115 offset:5544
	s_waitcnt vmcnt(9)
	ds_write_b32 v0, v116 offset:5808
	s_waitcnt vmcnt(8)
	ds_write_b32 v0, v117 offset:6072
	s_waitcnt vmcnt(7)
	ds_write_b32 v0, v118 offset:6336
	s_waitcnt vmcnt(6)
	ds_write_b32 v0, v119 offset:6600
	s_waitcnt vmcnt(5)
	ds_write_b32 v0, v120 offset:6864
	s_waitcnt vmcnt(4)
	ds_write_b32 v0, v121 offset:7128
	s_waitcnt vmcnt(3)
	ds_write_b32 v0, v122 offset:7392
	s_waitcnt vmcnt(2)
	ds_write_b32 v0, v123 offset:7656
	s_waitcnt vmcnt(1)
	ds_write_b32 v0, v124 offset:7920
	s_waitcnt vmcnt(0)
	ds_write_b32 v0, v125 offset:8184
	v_add_u32_e32 v0, 0x2100, v0
	s_add_i32 s1, s19, 0xffffe780
	s_lshr_b32 s62, s1, 9
	s_lshl_b32 s0, s19, 5
	s_and_b32 s0, s0, 0x3e0
	s_lshl_b64 s[4:5], s[62:63], 21
	s_add_u32 s4, s20, s4
	s_addc_u32 s5, s21, s5
	s_lshl_b32 s1, s1, 2
	s_and_b32 s1, s1, 0x780
	s_add_u32 s4, s4, s1
	s_waitcnt lgkmcnt(0)
; #define LAS __attribute__((address_space(3)))
; __device__ __forceinline__ unsigned pk2(float lo, float hi) { return f2bf(lo) | (f2bf(hi) << 16); }
; template <bool MAPPED>
; __device__ __forceinline__ void transpose_item(const float* W, int K, int Nsrc, bf16_t* WT, const float* gk, LAS float* scr, int item, int nblk, int lane) {
;     ...
;     asm volatile("s_waitcnt lgkmcnt(0)" ::: "memory");
;     const int c = lane & 7;
; #pragma unroll
;     for (int j = 0; j < 4; ++j) { const int n = (lane >> 3) + 8 * j; const LAS float* s = scr + (8 * c) * 33 + n;
;         u32x4 o; o.x = pk2(s[0 * 33], s[1 * 33]); o.y = pk2(s[2 * 33], s[3 * 33]); o.z = pk2(s[4 * 33], s[5 * 33]); o.w = pk2(s[6 * 33], s[7 * 33]);
;         *(u32x4*)(WT + (size_t)(j0 + n) * K + k0 + 8 * c) = o; }
;     asm volatile("s_waitcnt lgkmcnt(0)" ::: "memory");
	s_addc_u32 s5, s5, 0
	v_mov_b32_e32 v29, v1
	v_lshl_add_u64 v[30:31], s[4:5], 0, v[28:29]
	ds_read_b32 v0, v67
	ds_read_b32 v29, v67 offset:132
	s_waitcnt lgkmcnt(1)
	v_bfe_u32 v32, v0, 16, 1
	v_add3_u32 v0, v0, v32, s81
	s_waitcnt lgkmcnt(0)
	v_bfe_u32 v32, v29, 16, 1
	v_lshrrev_b32_e32 v0, 16, v0
	v_add3_u32 v29, v29, v32, s81
	v_and_or_b32 v32, v29, s46, v0
	ds_read_b32 v0, v67 offset:264
	ds_read_b32 v29, v67 offset:396
	s_waitcnt lgkmcnt(1)
	v_bfe_u32 v33, v0, 16, 1
	v_add3_u32 v0, v0, v33, s81
	s_waitcnt lgkmcnt(0)
	v_bfe_u32 v33, v29, 16, 1
	v_lshrrev_b32_e32 v0, 16, v0
	v_add3_u32 v29, v29, v33, s81
	v_and_or_b32 v33, v29, s46, v0
	ds_read_b32 v0, v67 offset:528
	ds_read_b32 v29, v67 offset:660
	s_waitcnt lgkmcnt(1)
	v_bfe_u32 v34, v0, 16, 1
	v_add3_u32 v0, v0, v34, s81
	s_waitcnt lgkmcnt(0)
	v_bfe_u32 v34, v29, 16, 1
	v_lshrrev_b32_e32 v0, 16, v0
	v_add3_u32 v29, v29, v34, s81
	v_and_or_b32 v34, v29, s46, v0
	ds_read_b32 v0, v67 offset:792
	ds_read_b32 v29, v67 offset:924
	s_waitcnt lgkmcnt(1)
	v_bfe_u32 v35, v0, 16, 1
	v_add3_u32 v0, v0, v35, s81
	s_waitcnt lgkmcnt(0)
	v_bfe_u32 v35, v29, 16, 1
	v_lshrrev_b32_e32 v0, 16, v0
	v_add3_u32 v29, v29, v35, s81
	v_and_or_b32 v35, v29, s46, v0
	v_or_b32_e32 v0, s0, v66
	v_lshlrev_b32_e32 v0, 11, v0
	v_lshl_add_u64 v[36:37], v[30:31], 0, v[0:1]
	flat_store_dwordx4 v[36:37], v[32:35]
	ds_read_b32 v0, v67 offset:32
	ds_read_b32 v29, v67 offset:164
	s_waitcnt lgkmcnt(0)
	v_bfe_u32 v32, v0, 16, 1
	v_add3_u32 v0, v0, v32, s81
	v_bfe_u32 v32, v29, 16, 1
	v_lshrrev_b32_e32 v0, 16, v0
	v_add3_u32 v29, v29, v32, s81
	v_and_or_b32 v32, v29, s46, v0
	ds_read_b32 v0, v67 offset:296
	ds_read_b32 v29, v67 offset:428
	s_waitcnt lgkmcnt(0)
	v_bfe_u32 v33, v0, 16, 1
	v_add3_u32 v0, v0, v33, s81
	v_bfe_u32 v33, v29, 16, 1
	v_lshrrev_b32_e32 v0, 16, v0
	v_add3_u32 v29, v29, v33, s81
	v_and_or_b32 v33, v29, s46, v0
	ds_read_b32 v0, v67 offset:560
	ds_read_b32 v29, v67 offset:692
	s_waitcnt lgkmcnt(0)
	v_bfe_u32 v34, v0, 16, 1
	v_add3_u32 v0, v0, v34, s81
	v_bfe_u32 v34, v29, 16, 1
	v_lshrrev_b32_e32 v0, 16, v0
	v_add3_u32 v29, v29, v34, s81
	v_and_or_b32 v34, v29, s46, v0
	ds_read_b32 v0, v67 offset:824
	ds_read_b32 v29, v67 offset:956
	s_waitcnt lgkmcnt(0)
	v_bfe_u32 v35, v0, 16, 1
	v_add3_u32 v0, v0, v35, s81
	v_bfe_u32 v35, v29, 16, 1
	v_lshrrev_b32_e32 v0, 16, v0
	v_add3_u32 v29, v29, v35, s81
	v_and_or_b32 v35, v29, s46, v0
	v_or_b32_e32 v0, s0, v68
	v_lshlrev_b32_e32 v0, 11, v0
	v_lshl_add_u64 v[36:37], v[30:31], 0, v[0:1]
	flat_store_dwordx4 v[36:37], v[32:35]
	ds_read_b32 v0, v67 offset:64
	ds_read_b32 v29, v67 offset:196
	s_waitcnt lgkmcnt(0)
	v_bfe_u32 v32, v0, 16, 1
	v_add3_u32 v0, v0, v32, s81
	v_bfe_u32 v32, v29, 16, 1
	v_lshrrev_b32_e32 v0, 16, v0
	v_add3_u32 v29, v29, v32, s81
	v_and_or_b32 v32, v29, s46, v0
	ds_read_b32 v0, v67 offset:328
	ds_read_b32 v29, v67 offset:460
	s_waitcnt lgkmcnt(0)
	v_bfe_u32 v33, v0, 16, 1
	v_add3_u32 v0, v0, v33, s81
	v_bfe_u32 v33, v29, 16, 1
	v_lshrrev_b32_e32 v0, 16, v0
	v_add3_u32 v29, v29, v33, s81
	v_and_or_b32 v33, v29, s46, v0
	ds_read_b32 v0, v67 offset:592
	ds_read_b32 v29, v67 offset:724
	s_waitcnt lgkmcnt(0)
	v_bfe_u32 v34, v0, 16, 1
	v_add3_u32 v0, v0, v34, s81
	v_bfe_u32 v34, v29, 16, 1
	v_lshrrev_b32_e32 v0, 16, v0
	v_add3_u32 v29, v29, v34, s81
	v_and_or_b32 v34, v29, s46, v0
	ds_read_b32 v0, v67 offset:856
	ds_read_b32 v29, v67 offset:988
	s_waitcnt lgkmcnt(0)
	v_bfe_u32 v35, v0, 16, 1
	v_add3_u32 v0, v0, v35, s81
	v_bfe_u32 v35, v29, 16, 1
	v_lshrrev_b32_e32 v0, 16, v0
	v_add3_u32 v29, v29, v35, s81
	v_and_or_b32 v35, v29, s46, v0
	v_or_b32_e32 v0, s0, v69
	v_lshlrev_b32_e32 v0, 11, v0
	v_lshl_add_u64 v[36:37], v[30:31], 0, v[0:1]
	flat_store_dwordx4 v[36:37], v[32:35]
	ds_read_b32 v0, v67 offset:96
	ds_read_b32 v29, v67 offset:228
	s_waitcnt lgkmcnt(0)
	v_bfe_u32 v32, v0, 16, 1
	v_add3_u32 v0, v0, v32, s81
	v_bfe_u32 v32, v29, 16, 1
	v_lshrrev_b32_e32 v0, 16, v0
	v_add3_u32 v29, v29, v32, s81
	v_and_or_b32 v32, v29, s46, v0
	ds_read_b32 v0, v67 offset:360
	ds_read_b32 v29, v67 offset:492
	s_waitcnt lgkmcnt(0)
	v_bfe_u32 v33, v0, 16, 1
	v_add3_u32 v0, v0, v33, s81
	v_bfe_u32 v33, v29, 16, 1
	v_lshrrev_b32_e32 v0, 16, v0
	v_add3_u32 v29, v29, v33, s81
	v_and_or_b32 v33, v29, s46, v0
	ds_read_b32 v0, v67 offset:624
	ds_read_b32 v29, v67 offset:756
	s_waitcnt lgkmcnt(0)
	v_bfe_u32 v34, v0, 16, 1
	v_add3_u32 v0, v0, v34, s81
	v_bfe_u32 v34, v29, 16, 1
	v_lshrrev_b32_e32 v0, 16, v0
	v_add3_u32 v29, v29, v34, s81
	v_and_or_b32 v34, v29, s46, v0
	ds_read_b32 v0, v67 offset:888
	ds_read_b32 v29, v67 offset:1020
	s_waitcnt lgkmcnt(0)
	v_bfe_u32 v35, v0, 16, 1
	v_add3_u32 v0, v0, v35, s81
	v_bfe_u32 v35, v29, 16, 1
	v_lshrrev_b32_e32 v0, 16, v0
	v_add3_u32 v29, v29, v35, s81
	v_and_or_b32 v35, v29, s46, v0
	v_or_b32_e32 v0, s0, v70
	v_lshlrev_b32_e32 v0, 11, v0
	v_lshl_add_u64 v[30:31], v[30:31], 0, v[0:1]
	flat_store_dwordx4 v[30:31], v[32:35]
	s_waitcnt lgkmcnt(0)

; #define LAS __attribute__((address_space(3)))
; template <bool MAPPED>
; __device__ __forceinline__ void transpose_item(const float* W, int K, int Nsrc, bf16_t* WT, const float* gk, LAS float* scr, int item, int nblk, int lane) {
;     const int kb = item / nblk, nb = item % nblk, k0 = 64 * kb, j0 = 32 * nb;
;     const int sc = MAPPED ? in_map(j0 + (lane & 31)) : (j0 + (lane & 31));
; #pragma unroll 8
;     for (int i = 0; i < 32; ++i) { const int kk = 2 * i + (lane >> 5); float v = (sc >= 0) ? W[(size_t)(k0 + kk) * Nsrc + sc] : 0.f; if (gk) v *= gk[k0 + kk]; scr[kk * 33 + (lane & 31)] = v; }
;     asm volatile("s_waitcnt lgkmcnt(0)" ::: "memory");
.LBB0_850:
	s_add_u32 s16, s16, 64
	s_addc_u32 s17, s17, 0
	v_lshl_add_u64 v[34:35], v[34:35], 0, s[92:93]
	v_lshl_add_u64 v[38:39], v[38:39], 0, s[92:93]
	v_lshl_add_u64 v[42:43], v[42:43], 0, s[92:93]
	v_lshl_add_u64 v[46:47], v[46:47], 0, s[92:93]
	v_lshl_add_u64 v[50:51], v[50:51], 0, s[92:93]
	v_lshl_add_u64 v[54:55], v[54:55], 0, s[92:93]
	v_lshl_add_u64 v[58:59], v[58:59], 0, s[92:93]
	v_lshl_add_u64 v[62:63], v[62:63], 0, s[92:93]
	v_add_u32_e32 v0, 0x1080, v0
	s_cmpk_lg_i32 s16, 0x100
	s_cbranch_scc0 .LBB0_798
.LBB0_851:
	v_cndmask_b32_e64 v79, 0, 1, s[8:9]
	v_cmp_ne_u32_e64 s[12:13], 1, v79
	s_andn2_b64 vcc, exec, s[8:9]
	s_cbranch_vccnz .Ltq1n
	v_lshl_add_u64 v[80:81], v[60:61], 0, s[16:17]
	global_load_dword v110, v[80:81], off
	v_lshl_add_u64 v[80:81], v[56:57], 0, s[16:17]
	global_load_dword v111, v[80:81], off
	v_lshl_add_u64 v[80:81], v[52:53], 0, s[16:17]
	global_load_dword v112, v[80:81], off
	v_lshl_add_u64 v[80:81], v[48:49], 0, s[16:17]
	global_load_dword v113, v[80:81], off
	v_lshl_add_u64 v[80:81], v[44:45], 0, s[16:17]
	global_load_dword v114, v[80:81], off
	v_lshl_add_u64 v[80:81], v[40:41], 0, s[16:17]
	global_load_dword v115, v[80:81], off
	v_lshl_add_u64 v[80:81], v[36:37], 0, s[16:17]
	global_load_dword v116, v[80:81], off
	v_lshl_add_u64 v[80:81], v[30:31], 0, s[16:17]
	global_load_dword v117, v[80:81], off
	v_lshl_add_u64 v[80:81], v[60:61], 0, s[16:17]
	global_load_dword v118, v[80:81], off offset:64
	v_lshl_add_u64 v[80:81], v[56:57], 0, s[16:17]
	global_load_dword v119, v[80:81], off offset:64
	v_lshl_add_u64 v[80:81], v[52:53], 0, s[16:17]
	global_load_dword v120, v[80:81], off offset:64
	v_lshl_add_u64 v[80:81], v[48:49], 0, s[16:17]
	global_load_dword v121, v[80:81], off offset:64
	v_lshl_add_u64 v[80:81], v[44:45], 0, s[16:17]
	global_load_dword v122, v[80:81], off offset:64
	v_lshl_add_u64 v[80:81], v[40:41], 0, s[16:17]
	global_load_dword v123, v[80:81], off offset:64
	v_lshl_add_u64 v[80:81], v[36:37], 0, s[16:17]
	global_load_dword v124, v[80:81], off offset:64
	v_lshl_add_u64 v[80:81], v[30:31], 0, s[16:17]
	global_load_dword v125, v[80:81], off offset:64
	v_mov_b32_e32 v90, 0
	v_mov_b32_e32 v91, 0
	v_mov_b32_e32 v92, 0
	v_mov_b32_e32 v93, 0
	v_mov_b32_e32 v94, 0
	v_mov_b32_e32 v95, 0
	v_mov_b32_e32 v96, 0
	v_mov_b32_e32 v97, 0
	s_and_saveexec_b64 s[0:1], s[10:11]
	s_cbranch_execz .Ltq1x0
	v_lshl_add_u64 v[80:81], v[62:63], 0, v[32:33]
	global_load_dword v90, v[80:81], off
	v_lshl_add_u64 v[80:81], v[58:59], 0, v[32:33]
	global_load_dword v91, v[80:81], off
	v_lshl_add_u64 v[80:81], v[54:55], 0, v[32:33]
	global_load_dword v92, v[80:81], off
	v_lshl_add_u64 v[80:81], v[50:51], 0, v[32:33]
	global_load_dword v93, v[80:81], off
	v_lshl_add_u64 v[80:81], v[46:47], 0, v[32:33]
	global_load_dword v94, v[80:81], off
	v_lshl_add_u64 v[80:81], v[42:43], 0, v[32:33]
	global_load_dword v95, v[80:81], off
	v_lshl_add_u64 v[80:81], v[38:39], 0, v[32:33]
	global_load_dword v96, v[80:81], off
	v_lshl_add_u64 v[80:81], v[34:35], 0, v[32:33]
	global_load_dword v97, v[80:81], off
.Ltq1x0:
	s_or_b64 exec, exec, s[0:1]
	s_add_u32 s16, s16, 64
	s_addc_u32 s17, s17, 0
	v_lshl_add_u64 v[34:35], v[34:35], 0, s[92:93]
	v_lshl_add_u64 v[38:39], v[38:39], 0, s[92:93]
	v_lshl_add_u64 v[42:43], v[42:43], 0, s[92:93]
	v_lshl_add_u64 v[46:47], v[46:47], 0, s[92:93]
	v_lshl_add_u64 v[50:51], v[50:51], 0, s[92:93]
	v_lshl_add_u64 v[54:55], v[54:55], 0, s[92:93]
	v_lshl_add_u64 v[58:59], v[58:59], 0, s[92:93]
	v_lshl_add_u64 v[62:63], v[62:63], 0, s[92:93]
	v_mov_b32_e32 v98, 0
	v_mov_b32_e32 v99, 0
	v_mov_b32_e32 v100, 0
	v_mov_b32_e32 v101, 0
	v_mov_b32_e32 v102, 0
	v_mov_b32_e32 v103, 0
	v_mov_b32_e32 v104, 0
	v_mov_b32_e32 v105, 0
	s_and_saveexec_b64 s[0:1], s[10:11]
	s_cbranch_execz .Ltq1x1
	v_lshl_add_u64 v[80:81], v[62:63], 0, v[32:33]
	global_load_dword v98, v[80:81], off
	v_lshl_add_u64 v[80:81], v[58:59], 0, v[32:33]
	global_load_dword v99, v[80:81], off
	v_lshl_add_u64 v[80:81], v[54:55], 0, v[32:33]
	global_load_dword v100, v[80:81], off
	v_lshl_add_u64 v[80:81], v[50:51], 0, v[32:33]
	global_load_dword v101, v[80:81], off
	v_lshl_add_u64 v[80:81], v[46:47], 0, v[32:33]
	global_load_dword v102, v[80:81], off
	v_lshl_add_u64 v[80:81], v[42:43], 0, v[32:33]
	global_load_dword v103, v[80:81], off
	v_lshl_add_u64 v[80:81], v[38:39], 0, v[32:33]
	global_load_dword v104, v[80:81], off
	v_lshl_add_u64 v[80:81], v[34:35], 0, v[32:33]
	global_load_dword v105, v[80:81], off
.Ltq1x1:
	s_or_b64 exec, exec, s[0:1]
	s_waitcnt vmcnt(15)
	v_mul_f32_e32 v90, v90, v110
	ds_write_b32 v0, v90
	s_waitcnt vmcnt(14)
	v_mul_f32_e32 v91, v91, v111
	ds_write_b32 v0, v91 offset:264
	s_waitcnt vmcnt(13)
	v_mul_f32_e32 v92, v92, v112
	ds_write_b32 v0, v92 offset:528
	s_waitcnt vmcnt(12)
	v_mul_f32_e32 v93, v93, v113
	ds_write_b32 v0, v93 offset:792
	s_waitcnt vmcnt(11)
	v_mul_f32_e32 v94, v94, v114
	ds_write_b32 v0, v94 offset:1056
	s_waitcnt vmcnt(10)
	v_mul_f32_e32 v95, v95, v115
	ds_write_b32 v0, v95 offset:1320
	s_waitcnt vmcnt(9)
	v_mul_f32_e32 v96, v96, v116
	ds_write_b32 v0, v96 offset:1584
	s_waitcnt vmcnt(8)
	v_mul_f32_e32 v97, v97, v117
	ds_write_b32 v0, v97 offset:1848
	s_waitcnt vmcnt(7)
	v_mul_f32_e32 v98, v98, v118
	ds_write_b32 v0, v98 offset:2112
	s_waitcnt vmcnt(6)
	v_mul_f32_e32 v99, v99, v119
	ds_write_b32 v0, v99 offset:2376
	s_waitcnt vmcnt(5)
	v_mul_f32_e32 v100, v100, v120
	ds_write_b32 v0, v100 offset:2640
	s_waitcnt vmcnt(4)
	v_mul_f32_e32 v101, v101, v121
	ds_write_b32 v0, v101 offset:2904
	s_waitcnt vmcnt(3)
	v_mul_f32_e32 v102, v102, v122
	ds_write_b32 v0, v102 offset:3168
	s_waitcnt vmcnt(2)
	v_mul_f32_e32 v103, v103, v123
	ds_write_b32 v0, v103 offset:3432
	s_waitcnt vmcnt(1)
	v_mul_f32_e32 v104, v104, v124
	ds_write_b32 v0, v104 offset:3696
	s_waitcnt vmcnt(0)
	v_mul_f32_e32 v105, v105, v125
	ds_write_b32 v0, v105 offset:3960
	s_branch .LBB0_850
.Ltq1n:
	v_mov_b32_e32 v90, 0
	v_mov_b32_e32 v91, 0
	v_mov_b32_e32 v92, 0
	v_mov_b32_e32 v93, 0
	v_mov_b32_e32 v94, 0
	v_mov_b32_e32 v95, 0
	v_mov_b32_e32 v96, 0
	v_mov_b32_e32 v97, 0
	s_and_saveexec_b64 s[0:1], s[10:11]
	s_cbranch_execz .Ltq1y0
	v_lshl_add_u64 v[80:81], v[62:63], 0, v[32:33]
	global_load_dword v90, v[80:81], off
	v_lshl_add_u64 v[80:81], v[58:59], 0, v[32:33]
	global_load_dword v91, v[80:81], off
	v_lshl_add_u64 v[80:81], v[54:55], 0, v[32:33]
	global_load_dword v92, v[80:81], off
	v_lshl_add_u64 v[80:81], v[50:51], 0, v[32:33]
	global_load_dword v93, v[80:81], off
	v_lshl_add_u64 v[80:81], v[46:47], 0, v[32:33]
	global_load_dword v94, v[80:81], off
	v_lshl_add_u64 v[80:81], v[42:43], 0, v[32:33]
	global_load_dword v95, v[80:81], off
	v_lshl_add_u64 v[80:81], v[38:39], 0, v[32:33]
	global_load_dword v96, v[80:81], off
	v_lshl_add_u64 v[80:81], v[34:35], 0, v[32:33]
	global_load_dword v97, v[80:81], off

; template <bool MAPPED>
; __device__ __forceinline__ void transpose_item(const float* W, int K, int Nsrc, bf16_t* WT, const float* gk, LAS float* scr, int item, int nblk, int lane) {
;     ...
;     for (int i = 0; i < 32; ++i) { const int kk = 2 * i + (lane >> 5); float v = (sc >= 0) ? W[(size_t)(k0 + kk) * Nsrc + sc] : 0.f; if (gk) v *= gk[k0 + kk]; scr[kk * 33 + (lane & 31)] = v; }
.Ltq1y1:
	s_or_b64 exec, exec, s[0:1]
	s_waitcnt vmcnt(15)
	ds_write_b32 v0, v90
	s_waitcnt vmcnt(14)
	ds_write_b32 v0, v91 offset:264
	s_waitcnt vmcnt(13)
	ds_write_b32 v0, v92 offset:528
	s_waitcnt vmcnt(12)
	ds_write_b32 v0, v93 offset:792
	s_waitcnt vmcnt(11)
	ds_write_b32 v0, v94 offset:1056
	s_waitcnt vmcnt(10)
	ds_write_b32 v0, v95 offset:1320
	s_waitcnt vmcnt(9)
	ds_write_b32 v0, v96 offset:1584
	s_waitcnt vmcnt(8)
	ds_write_b32 v0, v97 offset:1848
	s_waitcnt vmcnt(7)
	ds_write_b32 v0, v98 offset:2112
	s_waitcnt vmcnt(6)
	ds_write_b32 v0, v99 offset:2376
	s_waitcnt vmcnt(5)
	ds_write_b32 v0, v100 offset:2640
	s_waitcnt vmcnt(4)
	ds_write_b32 v0, v101 offset:2904
	s_waitcnt vmcnt(3)
	ds_write_b32 v0, v102 offset:3168
	s_waitcnt vmcnt(2)
	ds_write_b32 v0, v103 offset:3432
	s_waitcnt vmcnt(1)
	ds_write_b32 v0, v104 offset:3696
	s_waitcnt vmcnt(0)
	ds_write_b32 v0, v105 offset:3960
	s_branch .LBB0_850
